# unit_O (out-proj) k-loops role-split + software-pipelined like the other GEMMs: waves 0-3 issue all 17 LDS-DMA per K-tile with SALU addressing, waves 4-7 MFMA only
# speedup vs baseline: 1.1463x; 1.0213x over previous
; DI int opaque_tid() { int t = threadIdx.x; asm volatile("" : "+v"(t)); return t; }
;     constexpr int WM = BM / WR, WN = BN / WC, MT = WM / 16, NT = WN / 16, ROWS = BM + BN, NCH = ROWS * 4, NIT = (NCH + 511) / 512, BUF = ROWS * 64, KT = 32;
;     constexpr int NTS = NT / NSEG, D = NST - 1;
;     static_assert(D == 1 || (NCH % 512 == 0), "deep ring needs a uniform per-thread load count");
;     const int tid = opaque_tid(), lane = tid & 63, wid = tid >> 6, wr = wid / WC, wc = wid % WC, l15 = lane & 15, quad = lane >> 4;
;     const int lrow = tid >> 2, lc = tid & 3;
;     const int lcg = lc ^ ((0 - (tid >> 4)) & 3);
;     const int rsw = (quad ^ ((0 - (l15 >> 2)) & 3)) << 4;
; #pragma unroll
;     for (int mt = 0; mt < MT; ++mt)
; #pragma unroll
;         for (int nt = 0; nt < NT; ++nt) acc[mt][nt] = (f32x4){0.f, 0.f, 0.f, 0.f};
;     const unsigned loff = (unsigned)(lrow * 64 + lcg * 16);
;     const int koff = (int)((blockIdx.x >> 3) + (blockIdx.x & 7) * 4) & (KT - 1);
;     auto issue_one = [&](int kt, int b, int i) {
;         const int row = lrow + 128 * i;
;         if ((NCH % 512 == 0) || (i < NCH / 512) || row < ROWS) {
;             const int kq = (kt + koff) & (KT - 1);
;             const char* ua = (const char*)A + (size_t)((DBG & 1) ? 0 : kq) * (BM * 64);
;             const char* ub = (const char*)Bt + (size_t)((DBG & 2) ? 0 : kq) * ((size_t)ldbk * 2);
;             const char* src;
;             if (BM % 128 == 0) src = (i < BM / 128) ? (ua + i * 8192 + loff) : (ub + (i * 128 - BM) * 64 + loff);
;             else if (i == 0) src = (lrow < BM) ? (ua + loff) : (ub + loff - BM * 64);
;             else src = ub + (i * 128 - BM) * 64 + loff;
;             __builtin_amdgcn_global_load_lds((const unsigned*)src, (unsigned*)(lds + b * BUF + i * 8192 + tid * 16), 16, 0, 0);
;         }
;     };
.LBB0_96:
	s_or_b64 exec, exec, s[8:9]
	v_ashrrev_i32_e32 v3, 6, v2
	v_lshrrev_b32_e32 v4, 29, v3
	v_add_u32_e32 v4, v3, v4
	v_lshlrev_b32_e32 v6, 2, v2
	v_ashrrev_i32_e32 v4, 3, v4
	v_and_b32_e32 v6, 48, v6
	v_mul_i32_i24_e32 v5, 8, v4
	v_sub_u32_e32 v6, 0, v6
	v_sub_u32_e32 v3, v3, v5
	v_bitop3_b32 v5, v2, 48, v6 bitop3:0x48
	v_lshlrev_b32_e32 v2, 6, v2
	v_and_b32_e32 v2, 0x3c0, v2
	v_lshl_or_b32 v141, v3, 13, v2
	v_lshl_or_b32 v139, v4, 12, v2
	v_mov_b32_e32 v2, 0
	s_mov_b32 s8, 0
	v_add_u32_e32 v140, 0, v5
	v_lshl_add_u64 v[130:131], s[6:7], 0, v[0:1]
	v_lshl_add_u64 v[132:133], s[70:71], 0, v[0:1]
	s_mov_b32 s9, 1
	v_readlane_b32 s46, v243, 23
	s_mov_b32 s47, 1
	v_mov_b32_e32 v3, v2
	v_mov_b32_e32 v4, v2
	v_mov_b32_e32 v5, v2
	v_mov_b32_e32 v38, v2
	v_mov_b32_e32 v39, v2
	v_mov_b32_e32 v40, v2
	v_mov_b32_e32 v41, v2
	v_mov_b32_e32 v42, v2
	v_mov_b32_e32 v43, v2
	v_mov_b32_e32 v44, v2
	v_mov_b32_e32 v45, v2
	v_mov_b32_e32 v46, v2
	v_mov_b32_e32 v47, v2
	v_mov_b32_e32 v48, v2
	v_mov_b32_e32 v49, v2
	v_mov_b32_e32 v50, v2
	v_mov_b32_e32 v51, v2
	v_mov_b32_e32 v52, v2
	v_mov_b32_e32 v53, v2
	v_mov_b32_e32 v54, v2
	v_mov_b32_e32 v55, v2
	v_mov_b32_e32 v56, v2
	v_mov_b32_e32 v57, v2
	v_mov_b32_e32 v58, v2
	v_mov_b32_e32 v59, v2
	v_mov_b32_e32 v60, v2
	v_mov_b32_e32 v61, v2
	v_mov_b32_e32 v62, v2
	v_mov_b32_e32 v63, v2
	v_mov_b32_e32 v64, v2
	v_mov_b32_e32 v65, v2
	v_mov_b32_e32 v6, v2
	v_mov_b32_e32 v7, v2
	v_mov_b32_e32 v8, v2
	v_mov_b32_e32 v9, v2
	v_mov_b32_e32 v10, v2
	v_mov_b32_e32 v11, v2
	v_mov_b32_e32 v12, v2
	v_mov_b32_e32 v13, v2
	v_mov_b32_e32 v14, v2
	v_mov_b32_e32 v15, v2
	v_mov_b32_e32 v16, v2
	v_mov_b32_e32 v17, v2
	v_mov_b32_e32 v18, v2
	v_mov_b32_e32 v19, v2
	v_mov_b32_e32 v20, v2
	v_mov_b32_e32 v21, v2
	v_mov_b32_e32 v22, v2
	v_mov_b32_e32 v23, v2
	v_mov_b32_e32 v24, v2
	v_mov_b32_e32 v25, v2
	v_mov_b32_e32 v26, v2
	v_mov_b32_e32 v27, v2
	v_mov_b32_e32 v28, v2
	v_mov_b32_e32 v29, v2
	v_mov_b32_e32 v30, v2
	v_mov_b32_e32 v31, v2
	v_mov_b32_e32 v32, v2
	v_mov_b32_e32 v33, v2
	v_mov_b32_e32 v34, v2
	v_mov_b32_e32 v35, v2
	v_mov_b32_e32 v36, v2
	v_mov_b32_e32 v37, v2
	v_mov_b32_e32 v66, v2
	v_mov_b32_e32 v67, v2
	v_mov_b32_e32 v68, v2
	v_mov_b32_e32 v69, v2
	v_mov_b32_e32 v102, v2
	v_mov_b32_e32 v103, v2
	v_mov_b32_e32 v104, v2
	v_mov_b32_e32 v105, v2
	v_mov_b32_e32 v106, v2
	v_mov_b32_e32 v107, v2
	v_mov_b32_e32 v108, v2
	v_mov_b32_e32 v109, v2
	v_mov_b32_e32 v110, v2
	v_mov_b32_e32 v111, v2
	v_mov_b32_e32 v112, v2
	v_mov_b32_e32 v113, v2
	v_mov_b32_e32 v114, v2
	v_mov_b32_e32 v115, v2
	s_waitcnt lgkmcnt(0)
	v_mov_b32_e32 v116, v2
	v_mov_b32_e32 v117, v2
	v_mov_b32_e32 v118, v2
	v_mov_b32_e32 v119, v2
	v_mov_b32_e32 v120, v2
	v_mov_b32_e32 v121, v2
	v_mov_b32_e32 v122, v2
	v_mov_b32_e32 v123, v2
	v_mov_b32_e32 v124, v2
	v_mov_b32_e32 v125, v2
	v_mov_b32_e32 v126, v2
	v_mov_b32_e32 v127, v2
	v_mov_b32_e32 v128, v2
	v_mov_b32_e32 v129, v2
	v_mov_b32_e32 v70, v2
	v_mov_b32_e32 v71, v2
	v_mov_b32_e32 v72, v2
	v_mov_b32_e32 v73, v2
	v_mov_b32_e32 v74, v2
	v_mov_b32_e32 v75, v2
	v_mov_b32_e32 v76, v2
	v_mov_b32_e32 v77, v2
	v_mov_b32_e32 v78, v2
	v_mov_b32_e32 v79, v2
	v_mov_b32_e32 v80, v2
	v_mov_b32_e32 v81, v2
	v_mov_b32_e32 v82, v2
	v_mov_b32_e32 v83, v2
	v_mov_b32_e32 v84, v2
	v_mov_b32_e32 v85, v2
	v_mov_b32_e32 v86, v2
	v_mov_b32_e32 v87, v2
	v_mov_b32_e32 v88, v2
	v_mov_b32_e32 v89, v2
	v_mov_b32_e32 v90, v2
	v_mov_b32_e32 v91, v2
	v_mov_b32_e32 v92, v2
	v_mov_b32_e32 v93, v2
	v_mov_b32_e32 v94, v2
	v_mov_b32_e32 v95, v2
	v_mov_b32_e32 v96, v2
	v_mov_b32_e32 v97, v2
	v_mov_b32_e32 v98, v2
	v_mov_b32_e32 v99, v2
	v_mov_b32_e32 v100, v2
	v_mov_b32_e32 v101, v2
	v_readfirstlane_b32 s40, v212
	s_nop 3
	s_cmp_lt_u32 s40, 0x100
	s_cbranch_scc0 .Lpo1_c_entry
	s_cmp_lt_u32 s40, 0x80
	s_cselect_b32 s49, 1, 0
	s_lshl_b32 s46, s40, 4
	v_add_u32_e32 v199, s46, v0
	s_lshl_b32 s40, s40, 5
	v_readfirstlane_b32 s46, v130
	v_readfirstlane_b32 s47, v131
	v_readfirstlane_b32 s6, v0
	s_nop 3
	s_sub_u32 vcc_lo, s46, s6
	s_subb_u32 vcc_hi, s47, 0
	s_mov_b32 s9, 1
	s_add_i32 s46, s33, s9
	s_and_b32 s46, s46, 31
	s_lshl_b32 s6, s46, 16
	s_lshl_b32 s46, s46, 12
	s_add_u32 s46, vcc_lo, s46
	s_addc_u32 s47, vcc_hi, 0
	s_add_u32 s6, s70, s6
	s_addc_u32 s7, s71, 0
	s_sub_u32 s6, s6, 0x1000
	s_subb_u32 s7, s7, 0
	s_bitcmp1_b32 s9, 0
	s_cselect_b32 m0, 0x11000, 0
	s_add_u32 m0, m0, s40
	s_cmp_lg_u32 s49, 0
	s_cbranch_scc0 .Lpo1_s0b_1
	global_load_lds_dwordx4 v199, s[46:47]
	global_load_lds_dwordx4 v199, s[46:47] offset:1024
	s_branch .Lpo1_s0d_1
;     ...
;     auto issue_one = [&](int kt, int b, int i) {
;         const int row = lrow + 128 * i;
;         if ((NCH % 512 == 0) || (i < NCH / 512) || row < ROWS) {
;             const int kq = (kt + koff) & (KT - 1);
;             const char* ua = (const char*)A + (size_t)((DBG & 1) ? 0 : kq) * (BM * 64);
;             const char* ub = (const char*)Bt + (size_t)((DBG & 2) ? 0 : kq) * ((size_t)ldbk * 2);
;             const char* src;
;             if (BM % 128 == 0) src = (i < BM / 128) ? (ua + i * 8192 + loff) : (ub + (i * 128 - BM) * 64 + loff);
;             else if (i == 0) src = (lrow < BM) ? (ua + loff) : (ub + loff - BM * 64);
;             else src = ub + (i * 128 - BM) * 64 + loff;
;             __builtin_amdgcn_global_load_lds((const unsigned*)src, (unsigned*)(lds + b * BUF + i * 8192 + tid * 16), 16, 0, 0);
;         }
;     };
;     auto issue = [&](int kt, int b) {
; #pragma unroll
;         for (int i = 0; i < NIT; ++i) issue_one(kt, b, i);
;     };
;     auto compute = [&](int cb, bool do_issue, int ikt, int ib) {
;         const char* base = lds + cb * BUF;
;         bf16x8 af[MT], bfr[NT];
; #pragma unroll
;         for (int nt = 0; nt < NT; ++nt) {
;             const int br = BM + (nt / NTS) * (BN / NSEG) + wc * (NTS * 16) + (nt % NTS) * 16;
;             bfr[nt] = *(const bf16x8*)(base + (br + l15) * 64 + rsw);
;         }
; #pragma unroll
;         for (int mt = 0; mt < MT; ++mt) af[mt] = *(const bf16x8*)(base + (wr * WM + mt * 16 + l15) * 64 + rsw);
;         constexpr int TOT = MT * NT, PER = (TOT + NIT - 1) / NIT;
; #pragma unroll
;         for (int part = 0; part < NIT; ++part) {
; #pragma unroll
;             for (int q = 0; q < PER; ++q) {
;                 const int idx = part * PER + q;
;                 if (idx < TOT) {
;                     const int mt = idx / NT, nt = idx % NT;
;                     acc[mt][nt] = SWAP ? mfma16(bfr[nt], af[mt], acc[mt][nt]) : mfma16(af[mt], bfr[nt], acc[mt][nt]);
;                 }
;             }
;             __builtin_amdgcn_sched_barrier(0);
;             if (do_issue) issue_one(ikt, ib, part);
;             __builtin_amdgcn_sched_barrier(0);
;         }
;     };
;     __syncthreads();
; #pragma unroll
;     for (int d = 0; d < D; ++d) issue(d, d);
;     int cb = 0, ib = D;
;     for (int kt = 0; kt < KT; ++kt) {
.Lpo1_s0b_1:
	global_load_lds_dwordx4 v199, s[6:7]
	global_load_lds_dwordx4 v199, s[6:7] offset:1024
.Lpo1_s0d_1:
	s_add_u32 s6, s6, 0x2000
	s_addc_u32 s7, s7, 0
	s_add_u32 m0, m0, 0x2000
	s_nop 0
	global_load_lds_dwordx4 v199, s[6:7]
	global_load_lds_dwordx4 v199, s[6:7] offset:1024
	s_add_u32 s6, s6, 0x2000
	s_addc_u32 s7, s7, 0
	s_add_u32 m0, m0, 0x2000
	s_nop 0
	global_load_lds_dwordx4 v199, s[6:7]
	global_load_lds_dwordx4 v199, s[6:7] offset:1024
	s_add_u32 s6, s6, 0x2000
	s_addc_u32 s7, s7, 0
	s_add_u32 m0, m0, 0x2000
	s_nop 0
	global_load_lds_dwordx4 v199, s[6:7]
	global_load_lds_dwordx4 v199, s[6:7] offset:1024
	s_add_u32 s6, s6, 0x2000
	s_addc_u32 s7, s7, 0
	s_add_u32 m0, m0, 0x2000
	s_nop 0
	global_load_lds_dwordx4 v199, s[6:7]
	global_load_lds_dwordx4 v199, s[6:7] offset:1024
	s_add_u32 s6, s6, 0x2000
	s_addc_u32 s7, s7, 0
	s_add_u32 m0, m0, 0x2000
	s_nop 0
	global_load_lds_dwordx4 v199, s[6:7]
	global_load_lds_dwordx4 v199, s[6:7] offset:1024
	s_add_u32 s6, s6, 0x2000
	s_addc_u32 s7, s7, 0
	s_add_u32 m0, m0, 0x2000
	s_nop 0
	global_load_lds_dwordx4 v199, s[6:7]
	global_load_lds_dwordx4 v199, s[6:7] offset:1024
	s_add_u32 s6, s6, 0x2000
	s_addc_u32 s7, s7, 0
	s_add_u32 m0, m0, 0x2000
	s_nop 0
	global_load_lds_dwordx4 v199, s[6:7]
	global_load_lds_dwordx4 v199, s[6:7] offset:1024
	s_add_u32 s6, s6, 0x2000
	s_addc_u32 s7, s7, 0
	s_lshr_b32 s46, s40, 1
	s_bitcmp1_b32 s9, 0
	s_cselect_b32 m0, 0x11000, 0
	s_add_u32 m0, m0, s46
	s_add_u32 m0, m0, 0x10000
	s_nop 0
	global_load_lds_dwordx4 v0, s[6:7]
	s_mov_b32 s9, 2
	s_waitcnt vmcnt(17)
	s_barrier
	v_add_u32_e32 v197, v140, v141
	v_add_u32_e32 v196, v140, v139
	ds_read_b128 v[146:149], v196
	ds_read_b128 v[154:157], v196 offset:1024
	ds_read_b128 v[182:185], v196 offset:2048
	ds_read_b128 v[142:145], v197 offset:4096
	ds_read_b128 v[150:153], v197 offset:5120
	ds_read_b128 v[158:161], v197 offset:6144
	ds_read_b128 v[162:165], v197 offset:7168
	ds_read_b128 v[166:169], v197 offset:8192
	ds_read_b128 v[170:173], v197 offset:9216
	ds_read_b128 v[174:177], v197 offset:10240
	ds_read_b128 v[178:181], v197 offset:11264
	ds_read_b128 v[186:189], v196 offset:3072
.Lpo1_l_loop:
	s_bitcmp1_b32 s9, 0
	s_cselect_b32 s46, 0, 0x11000
	v_add_u32_e32 v198, s46, v140
	v_add_u32_e32 v197, v198, v141
	v_add_u32_e32 v196, v198, v139
	s_waitcnt lgkmcnt(8)
	v_mfma_f32_16x16x32_bf16 v[98:101], v[142:145], v[146:149], v[98:101]
	s_waitcnt lgkmcnt(7)
	v_mfma_f32_16x16x32_bf16 v[94:97], v[150:153], v[146:149], v[94:97]
	s_waitcnt lgkmcnt(6)
	v_mfma_f32_16x16x32_bf16 v[90:93], v[158:161], v[146:149], v[90:93]
	s_waitcnt lgkmcnt(5)
	v_mfma_f32_16x16x32_bf16 v[86:89], v[162:165], v[146:149], v[86:89]
	s_waitcnt lgkmcnt(4)
	v_mfma_f32_16x16x32_bf16 v[82:85], v[166:169], v[146:149], v[82:85]
	s_waitcnt lgkmcnt(3)
	v_mfma_f32_16x16x32_bf16 v[78:81], v[170:173], v[146:149], v[78:81]
	s_waitcnt lgkmcnt(2)
	v_mfma_f32_16x16x32_bf16 v[74:77], v[174:177], v[146:149], v[74:77]
	s_waitcnt lgkmcnt(1)
	v_mfma_f32_16x16x32_bf16 v[70:73], v[178:181], v[146:149], v[70:73]
	s_waitcnt vmcnt(0) lgkmcnt(0)
	s_barrier
	ds_read_b128 v[146:149], v196
	s_add_i32 s46, s33, s9
	s_and_b32 s46, s46, 31
	s_lshl_b32 s6, s46, 16
	s_lshl_b32 s46, s46, 12
	s_add_u32 s46, vcc_lo, s46
	s_addc_u32 s47, vcc_hi, 0
	s_add_u32 s6, s70, s6
	s_addc_u32 s7, s71, 0
	s_sub_u32 s6, s6, 0x1000
	s_subb_u32 s7, s7, 0
	s_bitcmp1_b32 s9, 0
	s_cselect_b32 m0, 0x11000, 0
	s_add_u32 m0, m0, s40
	s_cmp_lg_u32 s49, 0
	s_cbranch_scc0 .Lpo1_s0b_2
	global_load_lds_dwordx4 v199, s[46:47]
	global_load_lds_dwordx4 v199, s[46:47] offset:1024
	s_branch .Lpo1_s0d_2

; DI f32x4 mfma16(bf16x8 a, bf16x8 b, f32x4 c) { return __builtin_amdgcn_mfma_f32_16x16x32_bf16(a, b, c, 0, 0, 0); }
; template <int N> DI void wait_vm() { asm volatile("s_waitcnt vmcnt(%0)" ::"n"(N) : "memory"); }
; DI void raw_barrier() { asm volatile("" ::: "memory"); __builtin_amdgcn_s_barrier(); asm volatile("" ::: "memory"); }
;     ...
;     auto compute = [&](int cb, bool do_issue, int ikt, int ib) {
;         const char* base = lds + cb * BUF;
;         bf16x8 af[MT], bfr[NT];
; #pragma unroll
;         for (int nt = 0; nt < NT; ++nt) {
;             const int br = BM + (nt / NTS) * (BN / NSEG) + wc * (NTS * 16) + (nt % NTS) * 16;
;             bfr[nt] = *(const bf16x8*)(base + (br + l15) * 64 + rsw);
;         }
; #pragma unroll
;         for (int mt = 0; mt < MT; ++mt) af[mt] = *(const bf16x8*)(base + (wr * WM + mt * 16 + l15) * 64 + rsw);
;         constexpr int TOT = MT * NT, PER = (TOT + NIT - 1) / NIT;
; #pragma unroll
;         for (int part = 0; part < NIT; ++part) {
; #pragma unroll
;             for (int q = 0; q < PER; ++q) {
;                 const int idx = part * PER + q;
;                 if (idx < TOT) {
;                     const int mt = idx / NT, nt = idx % NT;
;                     acc[mt][nt] = SWAP ? mfma16(bfr[nt], af[mt], acc[mt][nt]) : mfma16(af[mt], bfr[nt], acc[mt][nt]);
;                 }
;             }
;             __builtin_amdgcn_sched_barrier(0);
;             if (do_issue) issue_one(ikt, ib, part);
;             __builtin_amdgcn_sched_barrier(0);
;         }
;     };
;     __syncthreads();
; #pragma unroll
;     for (int d = 0; d < D; ++d) issue(d, d);
;     int cb = 0, ib = D;
;     for (int kt = 0; kt < KT; ++kt) {
;         if (D > 1 && kt + D - 1 < KT) wait_vm<(D - 1) * NIT>(); else wait_vm<0>();
;         raw_barrier();
;         compute(cb, kt + D < KT, kt + D, ib);
;         cb = (cb + 1 == NST) ? 0 : cb + 1;
;         ib = (ib + 1 == NST) ? 0 : ib + 1;
;     }
.Lpo1_s0d_2:
	v_mfma_f32_16x16x32_bf16 v[126:129], v[142:145], v[154:157], v[126:129]
	v_mfma_f32_16x16x32_bf16 v[122:125], v[150:153], v[154:157], v[122:125]
	v_mfma_f32_16x16x32_bf16 v[118:121], v[158:161], v[154:157], v[118:121]
	s_add_u32 s6, s6, 0x2000
	s_addc_u32 s7, s7, 0
	s_add_u32 m0, m0, 0x2000
	s_nop 0
	global_load_lds_dwordx4 v199, s[6:7]
	global_load_lds_dwordx4 v199, s[6:7] offset:1024
	v_mfma_f32_16x16x32_bf16 v[114:117], v[162:165], v[154:157], v[114:117]
	v_mfma_f32_16x16x32_bf16 v[110:113], v[166:169], v[154:157], v[110:113]
	s_add_u32 s6, s6, 0x2000
	s_addc_u32 s7, s7, 0
	s_add_u32 m0, m0, 0x2000
	s_nop 0
	global_load_lds_dwordx4 v199, s[6:7]
	global_load_lds_dwordx4 v199, s[6:7] offset:1024
	v_mfma_f32_16x16x32_bf16 v[106:109], v[170:173], v[154:157], v[106:109]
	v_mfma_f32_16x16x32_bf16 v[102:105], v[174:177], v[154:157], v[102:105]
	v_mfma_f32_16x16x32_bf16 v[66:69], v[178:181], v[154:157], v[66:69]
	s_add_u32 s6, s6, 0x2000
	s_addc_u32 s7, s7, 0
	s_add_u32 m0, m0, 0x2000
	s_nop 0
	global_load_lds_dwordx4 v199, s[6:7]
	global_load_lds_dwordx4 v199, s[6:7] offset:1024
	ds_read_b128 v[154:157], v196 offset:1024
	v_mfma_f32_16x16x32_bf16 v[34:37], v[142:145], v[182:185], v[34:37]
	v_mfma_f32_16x16x32_bf16 v[30:33], v[150:153], v[182:185], v[30:33]
	v_mfma_f32_16x16x32_bf16 v[26:29], v[158:161], v[182:185], v[26:29]
	s_add_u32 s6, s6, 0x2000
	s_addc_u32 s7, s7, 0
	s_add_u32 m0, m0, 0x2000
	s_nop 0
	global_load_lds_dwordx4 v199, s[6:7]
	global_load_lds_dwordx4 v199, s[6:7] offset:1024
	v_mfma_f32_16x16x32_bf16 v[22:25], v[162:165], v[182:185], v[22:25]
	v_mfma_f32_16x16x32_bf16 v[18:21], v[166:169], v[182:185], v[18:21]
	s_add_u32 s6, s6, 0x2000
	s_addc_u32 s7, s7, 0
	s_add_u32 m0, m0, 0x2000
	s_nop 0
	global_load_lds_dwordx4 v199, s[6:7]
	global_load_lds_dwordx4 v199, s[6:7] offset:1024
	v_mfma_f32_16x16x32_bf16 v[14:17], v[170:173], v[182:185], v[14:17]
	v_mfma_f32_16x16x32_bf16 v[10:13], v[174:177], v[182:185], v[10:13]
	v_mfma_f32_16x16x32_bf16 v[6:9], v[178:181], v[182:185], v[6:9]
	s_add_u32 s6, s6, 0x2000
	s_addc_u32 s7, s7, 0
	s_add_u32 m0, m0, 0x2000
	s_nop 0
	global_load_lds_dwordx4 v199, s[6:7]
	global_load_lds_dwordx4 v199, s[6:7] offset:1024
	ds_read_b128 v[182:185], v196 offset:2048
	v_mfma_f32_16x16x32_bf16 v[62:65], v[142:145], v[186:189], v[62:65]
	ds_read_b128 v[142:145], v197 offset:4096
	v_mfma_f32_16x16x32_bf16 v[58:61], v[150:153], v[186:189], v[58:61]
	ds_read_b128 v[150:153], v197 offset:5120
	v_mfma_f32_16x16x32_bf16 v[54:57], v[158:161], v[186:189], v[54:57]
	ds_read_b128 v[158:161], v197 offset:6144
	s_add_u32 s6, s6, 0x2000
	s_addc_u32 s7, s7, 0
	s_add_u32 m0, m0, 0x2000
	s_nop 0
	global_load_lds_dwordx4 v199, s[6:7]
	global_load_lds_dwordx4 v199, s[6:7] offset:1024
	v_mfma_f32_16x16x32_bf16 v[50:53], v[162:165], v[186:189], v[50:53]
	ds_read_b128 v[162:165], v197 offset:7168
	v_mfma_f32_16x16x32_bf16 v[46:49], v[166:169], v[186:189], v[46:49]
	ds_read_b128 v[166:169], v197 offset:8192
	s_add_u32 s6, s6, 0x2000
	s_addc_u32 s7, s7, 0
	s_lshr_b32 s46, s40, 1
	s_bitcmp1_b32 s9, 0
	s_cselect_b32 m0, 0x11000, 0
	s_add_u32 m0, m0, s46
	s_add_u32 m0, m0, 0x10000
	s_nop 0
	global_load_lds_dwordx4 v0, s[6:7]
	v_mfma_f32_16x16x32_bf16 v[42:45], v[170:173], v[186:189], v[42:45]
	ds_read_b128 v[170:173], v197 offset:9216
	v_mfma_f32_16x16x32_bf16 v[38:41], v[174:177], v[186:189], v[38:41]
	ds_read_b128 v[174:177], v197 offset:10240
	v_mfma_f32_16x16x32_bf16 v[2:5], v[178:181], v[186:189], v[2:5]
	ds_read_b128 v[178:181], v197 offset:11264
	ds_read_b128 v[186:189], v196 offset:3072
	s_add_i32 s9, s9, 1
	s_cmp_lg_u32 s9, 32
	s_cbranch_scc1 .Lpo1_l_loop
	s_waitcnt lgkmcnt(8)
	v_mfma_f32_16x16x32_bf16 v[98:101], v[142:145], v[146:149], v[98:101]
	s_waitcnt lgkmcnt(7)
	v_mfma_f32_16x16x32_bf16 v[94:97], v[150:153], v[146:149], v[94:97]
	s_waitcnt lgkmcnt(6)
	v_mfma_f32_16x16x32_bf16 v[90:93], v[158:161], v[146:149], v[90:93]
	s_waitcnt lgkmcnt(5)
	v_mfma_f32_16x16x32_bf16 v[86:89], v[162:165], v[146:149], v[86:89]
	s_waitcnt lgkmcnt(4)
	v_mfma_f32_16x16x32_bf16 v[82:85], v[166:169], v[146:149], v[82:85]
	s_waitcnt lgkmcnt(3)
	v_mfma_f32_16x16x32_bf16 v[78:81], v[170:173], v[146:149], v[78:81]
	s_waitcnt lgkmcnt(2)
	v_mfma_f32_16x16x32_bf16 v[74:77], v[174:177], v[146:149], v[74:77]
	s_waitcnt lgkmcnt(1)
	v_mfma_f32_16x16x32_bf16 v[70:73], v[178:181], v[146:149], v[70:73]
	s_waitcnt lgkmcnt(0)
	v_mfma_f32_16x16x32_bf16 v[126:129], v[142:145], v[154:157], v[126:129]
	v_mfma_f32_16x16x32_bf16 v[122:125], v[150:153], v[154:157], v[122:125]
	v_mfma_f32_16x16x32_bf16 v[118:121], v[158:161], v[154:157], v[118:121]
	v_mfma_f32_16x16x32_bf16 v[114:117], v[162:165], v[154:157], v[114:117]
	v_mfma_f32_16x16x32_bf16 v[110:113], v[166:169], v[154:157], v[110:113]
	v_mfma_f32_16x16x32_bf16 v[106:109], v[170:173], v[154:157], v[106:109]
	v_mfma_f32_16x16x32_bf16 v[102:105], v[174:177], v[154:157], v[102:105]
	v_mfma_f32_16x16x32_bf16 v[66:69], v[178:181], v[154:157], v[66:69]
	v_mfma_f32_16x16x32_bf16 v[34:37], v[142:145], v[182:185], v[34:37]
	v_mfma_f32_16x16x32_bf16 v[30:33], v[150:153], v[182:185], v[30:33]
	v_mfma_f32_16x16x32_bf16 v[26:29], v[158:161], v[182:185], v[26:29]
	v_mfma_f32_16x16x32_bf16 v[22:25], v[162:165], v[182:185], v[22:25]
	v_mfma_f32_16x16x32_bf16 v[18:21], v[166:169], v[182:185], v[18:21]
	v_mfma_f32_16x16x32_bf16 v[14:17], v[170:173], v[182:185], v[14:17]
	v_mfma_f32_16x16x32_bf16 v[10:13], v[174:177], v[182:185], v[10:13]
	v_mfma_f32_16x16x32_bf16 v[6:9], v[178:181], v[182:185], v[6:9]
	v_mfma_f32_16x16x32_bf16 v[62:65], v[142:145], v[186:189], v[62:65]
	v_mfma_f32_16x16x32_bf16 v[58:61], v[150:153], v[186:189], v[58:61]
	v_mfma_f32_16x16x32_bf16 v[54:57], v[158:161], v[186:189], v[54:57]
	v_mfma_f32_16x16x32_bf16 v[50:53], v[162:165], v[186:189], v[50:53]
	v_mfma_f32_16x16x32_bf16 v[46:49], v[166:169], v[186:189], v[46:49]
	v_mfma_f32_16x16x32_bf16 v[42:45], v[170:173], v[186:189], v[42:45]
	v_mfma_f32_16x16x32_bf16 v[38:41], v[174:177], v[186:189], v[38:41]
	v_mfma_f32_16x16x32_bf16 v[2:5], v[178:181], v[186:189], v[2:5]
	s_branch .Lpo1_join
; DI f32x4 mfma16(bf16x8 a, bf16x8 b, f32x4 c) { return __builtin_amdgcn_mfma_f32_16x16x32_bf16(a, b, c, 0, 0, 0); }
; template <int N> DI void wait_vm() { asm volatile("s_waitcnt vmcnt(%0)" ::"n"(N) : "memory"); }
; DI void raw_barrier() { asm volatile("" ::: "memory"); __builtin_amdgcn_s_barrier(); asm volatile("" ::: "memory"); }
;     ...
;     auto compute = [&](int cb, bool do_issue, int ikt, int ib) {
;         const char* base = lds + cb * BUF;
;         bf16x8 af[MT], bfr[NT];
; #pragma unroll
;         for (int nt = 0; nt < NT; ++nt) {
;             const int br = BM + (nt / NTS) * (BN / NSEG) + wc * (NTS * 16) + (nt % NTS) * 16;
;             bfr[nt] = *(const bf16x8*)(base + (br + l15) * 64 + rsw);
;         }
; #pragma unroll
;         for (int mt = 0; mt < MT; ++mt) af[mt] = *(const bf16x8*)(base + (wr * WM + mt * 16 + l15) * 64 + rsw);
;         constexpr int TOT = MT * NT, PER = (TOT + NIT - 1) / NIT;
; #pragma unroll
;         for (int part = 0; part < NIT; ++part) {
; #pragma unroll
;             for (int q = 0; q < PER; ++q) {
;                 const int idx = part * PER + q;
;                 if (idx < TOT) {
;                     const int mt = idx / NT, nt = idx % NT;
;                     acc[mt][nt] = SWAP ? mfma16(bfr[nt], af[mt], acc[mt][nt]) : mfma16(af[mt], bfr[nt], acc[mt][nt]);
;                 }
;             }
;             __builtin_amdgcn_sched_barrier(0);
;             if (do_issue) issue_one(ikt, ib, part);
;             __builtin_amdgcn_sched_barrier(0);
;         }
;     };
;     __syncthreads();
; #pragma unroll
;     for (int d = 0; d < D; ++d) issue(d, d);
;     int cb = 0, ib = D;
;     for (int kt = 0; kt < KT; ++kt) {
;         if (D > 1 && kt + D - 1 < KT) wait_vm<(D - 1) * NIT>(); else wait_vm<0>();
;         raw_barrier();
;         compute(cb, kt + D < KT, kt + D, ib);
;         cb = (cb + 1 == NST) ? 0 : cb + 1;
;         ib = (ib + 1 == NST) ? 0 : ib + 1;
;     }
.Lpo1_c_entry:
	s_mov_b32 s9, 2
	s_waitcnt vmcnt(0)
	s_barrier
	v_add_u32_e32 v197, v140, v141
	v_add_u32_e32 v196, v140, v139
	ds_read_b128 v[146:149], v196
	ds_read_b128 v[154:157], v196 offset:1024
	ds_read_b128 v[182:185], v196 offset:2048
	ds_read_b128 v[142:145], v197 offset:4096
	ds_read_b128 v[150:153], v197 offset:5120
	ds_read_b128 v[158:161], v197 offset:6144
	ds_read_b128 v[162:165], v197 offset:7168
	ds_read_b128 v[166:169], v197 offset:8192
	ds_read_b128 v[170:173], v197 offset:9216
	ds_read_b128 v[174:177], v197 offset:10240
	ds_read_b128 v[178:181], v197 offset:11264
	ds_read_b128 v[186:189], v196 offset:3072
.Lpo1_c_loop:
	s_bitcmp1_b32 s9, 0
	s_cselect_b32 s46, 0, 0x11000
	v_add_u32_e32 v198, s46, v140
	v_add_u32_e32 v197, v198, v141
	v_add_u32_e32 v196, v198, v139
	s_waitcnt lgkmcnt(8)
	v_mfma_f32_16x16x32_bf16 v[98:101], v[142:145], v[146:149], v[98:101]
	s_waitcnt lgkmcnt(7)
	v_mfma_f32_16x16x32_bf16 v[94:97], v[150:153], v[146:149], v[94:97]
	s_waitcnt lgkmcnt(6)
	v_mfma_f32_16x16x32_bf16 v[90:93], v[158:161], v[146:149], v[90:93]
	s_waitcnt lgkmcnt(5)
	v_mfma_f32_16x16x32_bf16 v[86:89], v[162:165], v[146:149], v[86:89]
	s_waitcnt lgkmcnt(4)
	v_mfma_f32_16x16x32_bf16 v[82:85], v[166:169], v[146:149], v[82:85]
	s_waitcnt lgkmcnt(3)
	v_mfma_f32_16x16x32_bf16 v[78:81], v[170:173], v[146:149], v[78:81]
	s_waitcnt lgkmcnt(2)
	v_mfma_f32_16x16x32_bf16 v[74:77], v[174:177], v[146:149], v[74:77]
	s_waitcnt lgkmcnt(1)
	v_mfma_f32_16x16x32_bf16 v[70:73], v[178:181], v[146:149], v[70:73]
	s_waitcnt vmcnt(0) lgkmcnt(0)
	s_barrier
	ds_read_b128 v[146:149], v196
	v_mfma_f32_16x16x32_bf16 v[126:129], v[142:145], v[154:157], v[126:129]
	v_mfma_f32_16x16x32_bf16 v[122:125], v[150:153], v[154:157], v[122:125]
	v_mfma_f32_16x16x32_bf16 v[118:121], v[158:161], v[154:157], v[118:121]
	v_mfma_f32_16x16x32_bf16 v[114:117], v[162:165], v[154:157], v[114:117]
	v_mfma_f32_16x16x32_bf16 v[110:113], v[166:169], v[154:157], v[110:113]
	v_mfma_f32_16x16x32_bf16 v[106:109], v[170:173], v[154:157], v[106:109]
	v_mfma_f32_16x16x32_bf16 v[102:105], v[174:177], v[154:157], v[102:105]
	v_mfma_f32_16x16x32_bf16 v[66:69], v[178:181], v[154:157], v[66:69]
	ds_read_b128 v[154:157], v196 offset:1024
	v_mfma_f32_16x16x32_bf16 v[34:37], v[142:145], v[182:185], v[34:37]
	v_mfma_f32_16x16x32_bf16 v[30:33], v[150:153], v[182:185], v[30:33]
	v_mfma_f32_16x16x32_bf16 v[26:29], v[158:161], v[182:185], v[26:29]
	v_mfma_f32_16x16x32_bf16 v[22:25], v[162:165], v[182:185], v[22:25]
	v_mfma_f32_16x16x32_bf16 v[18:21], v[166:169], v[182:185], v[18:21]
	v_mfma_f32_16x16x32_bf16 v[14:17], v[170:173], v[182:185], v[14:17]
	v_mfma_f32_16x16x32_bf16 v[10:13], v[174:177], v[182:185], v[10:13]
	v_mfma_f32_16x16x32_bf16 v[6:9], v[178:181], v[182:185], v[6:9]
	ds_read_b128 v[182:185], v196 offset:2048
	v_mfma_f32_16x16x32_bf16 v[62:65], v[142:145], v[186:189], v[62:65]
	ds_read_b128 v[142:145], v197 offset:4096
	v_mfma_f32_16x16x32_bf16 v[58:61], v[150:153], v[186:189], v[58:61]
	ds_read_b128 v[150:153], v197 offset:5120
	v_mfma_f32_16x16x32_bf16 v[54:57], v[158:161], v[186:189], v[54:57]
	ds_read_b128 v[158:161], v197 offset:6144
	v_mfma_f32_16x16x32_bf16 v[50:53], v[162:165], v[186:189], v[50:53]
	ds_read_b128 v[162:165], v197 offset:7168
	v_mfma_f32_16x16x32_bf16 v[46:49], v[166:169], v[186:189], v[46:49]
	ds_read_b128 v[166:169], v197 offset:8192
	v_mfma_f32_16x16x32_bf16 v[42:45], v[170:173], v[186:189], v[42:45]
	ds_read_b128 v[170:173], v197 offset:9216
	v_mfma_f32_16x16x32_bf16 v[38:41], v[174:177], v[186:189], v[38:41]
	ds_read_b128 v[174:177], v197 offset:10240
	v_mfma_f32_16x16x32_bf16 v[2:5], v[178:181], v[186:189], v[2:5]
	ds_read_b128 v[178:181], v197 offset:11264
	ds_read_b128 v[186:189], v196 offset:3072
	s_add_i32 s9, s9, 1
	s_cmp_lg_u32 s9, 32
	s_cbranch_scc1 .Lpo1_c_loop
	s_waitcnt lgkmcnt(8)
	v_mfma_f32_16x16x32_bf16 v[98:101], v[142:145], v[146:149], v[98:101]
	s_waitcnt lgkmcnt(7)
	v_mfma_f32_16x16x32_bf16 v[94:97], v[150:153], v[146:149], v[94:97]
	s_waitcnt lgkmcnt(6)
	v_mfma_f32_16x16x32_bf16 v[90:93], v[158:161], v[146:149], v[90:93]
	s_waitcnt lgkmcnt(5)
	v_mfma_f32_16x16x32_bf16 v[86:89], v[162:165], v[146:149], v[86:89]
	s_waitcnt lgkmcnt(4)
	v_mfma_f32_16x16x32_bf16 v[82:85], v[166:169], v[146:149], v[82:85]
	s_waitcnt lgkmcnt(3)
	v_mfma_f32_16x16x32_bf16 v[78:81], v[170:173], v[146:149], v[78:81]
	s_waitcnt lgkmcnt(2)
	v_mfma_f32_16x16x32_bf16 v[74:77], v[174:177], v[146:149], v[74:77]
	s_waitcnt lgkmcnt(1)
	v_mfma_f32_16x16x32_bf16 v[70:73], v[178:181], v[146:149], v[70:73]
	s_waitcnt lgkmcnt(0)
	v_mfma_f32_16x16x32_bf16 v[126:129], v[142:145], v[154:157], v[126:129]
	v_mfma_f32_16x16x32_bf16 v[122:125], v[150:153], v[154:157], v[122:125]
	v_mfma_f32_16x16x32_bf16 v[118:121], v[158:161], v[154:157], v[118:121]
	v_mfma_f32_16x16x32_bf16 v[114:117], v[162:165], v[154:157], v[114:117]
	v_mfma_f32_16x16x32_bf16 v[110:113], v[166:169], v[154:157], v[110:113]
	v_mfma_f32_16x16x32_bf16 v[106:109], v[170:173], v[154:157], v[106:109]
	v_mfma_f32_16x16x32_bf16 v[102:105], v[174:177], v[154:157], v[102:105]
	v_mfma_f32_16x16x32_bf16 v[66:69], v[178:181], v[154:157], v[66:69]
	v_mfma_f32_16x16x32_bf16 v[34:37], v[142:145], v[182:185], v[34:37]
	v_mfma_f32_16x16x32_bf16 v[30:33], v[150:153], v[182:185], v[30:33]
	v_mfma_f32_16x16x32_bf16 v[26:29], v[158:161], v[182:185], v[26:29]
	v_mfma_f32_16x16x32_bf16 v[22:25], v[162:165], v[182:185], v[22:25]
	v_mfma_f32_16x16x32_bf16 v[18:21], v[166:169], v[182:185], v[18:21]
	v_mfma_f32_16x16x32_bf16 v[14:17], v[170:173], v[182:185], v[14:17]
	v_mfma_f32_16x16x32_bf16 v[10:13], v[174:177], v[182:185], v[10:13]
	v_mfma_f32_16x16x32_bf16 v[6:9], v[178:181], v[182:185], v[6:9]
	v_mfma_f32_16x16x32_bf16 v[62:65], v[142:145], v[186:189], v[62:65]
	v_mfma_f32_16x16x32_bf16 v[58:61], v[150:153], v[186:189], v[58:61]
	v_mfma_f32_16x16x32_bf16 v[54:57], v[158:161], v[186:189], v[54:57]
	v_mfma_f32_16x16x32_bf16 v[50:53], v[162:165], v[186:189], v[50:53]
	v_mfma_f32_16x16x32_bf16 v[46:49], v[166:169], v[186:189], v[46:49]
	v_mfma_f32_16x16x32_bf16 v[42:45], v[170:173], v[186:189], v[42:45]
	v_mfma_f32_16x16x32_bf16 v[38:41], v[174:177], v[186:189], v[38:41]
	v_mfma_f32_16x16x32_bf16 v[2:5], v[178:181], v[186:189], v[2:5]
; template <int N> DI void wait_vm() { asm volatile("s_waitcnt vmcnt(%0)" ::"n"(N) : "memory"); }
; DI void raw_barrier() { asm volatile("" ::: "memory"); __builtin_amdgcn_s_barrier(); asm volatile("" ::: "memory"); }
;     ...
;     __syncthreads();
; #pragma unroll
;     for (int d = 0; d < D; ++d) issue(d, d);
;     int cb = 0, ib = D;
;     for (int kt = 0; kt < KT; ++kt) {
;         if (D > 1 && kt + D - 1 < KT) wait_vm<(D - 1) * NIT>(); else wait_vm<0>();
;         raw_barrier();
;         compute(cb, kt + D < KT, kt + D, ib);
;         cb = (cb + 1 == NST) ? 0 : cb + 1;
;         ib = (ib + 1 == NST) ? 0 : ib + 1;
;     }
;     __syncthreads();
; DI void unit_O(const Params& p, char* lds, int l, int tile, int glu_tiles, int tile_b) {
;     ...
;     gemm_main<64, 1024, 1, 8, 1, true, 2>(WS_PTR(const bf16_t, OFF_Y) + (size_t)tile * 64 * 1024, WS_PTR(const bf16_t, OFF_WOUT) + (size_t)l * 1024 * 1024, 1024 * 32, lds, acc);
;     const float* xres = (l == 0) ? p.x : WS_PTR(const float, OFF_X1);
;     const size_t r0 = (size_t)tile * 64;
;     char* XR = lds;
;     float* GB = (float*)(lds + 131072);
;     float* red = (float*)(lds + 139264);
;     const int xrot = (int)(((blockIdx.x >> 3) + (blockIdx.x & 7) * 4) & 31) * 4;
;     const bf16_t* xbres = WS_PTR(const bf16_t, OFF_XB1) + ((size_t)((tile >> 1) * 32) * 128 + (tile & 1) * 64) * 32;
.Lpo1_join:
.LBB0_100:
	s_waitcnt vmcnt(0)
	v_add_u32_e32 v0, 0x11000, v140
	s_barrier
	v_add_u32_e32 v134, v0, v141
	v_add_u32_e32 v0, v0, v139
	ds_read_b128 v[130:133], v134 offset:4096
	ds_read_b128 v[138:141], v0
	ds_read_b128 v[142:145], v134 offset:5120
	ds_read_b128 v[146:149], v0 offset:1024
	ds_read_b128 v[150:153], v134 offset:6144
	ds_read_b128 v[154:157], v134 offset:7168
	ds_read_b128 v[158:161], v134 offset:8192
	ds_read_b128 v[162:165], v134 offset:9216
	ds_read_b128 v[166:169], v134 offset:10240
	ds_read_b128 v[170:173], v134 offset:11264
	ds_read_b128 v[174:177], v0 offset:2048
	ds_read_b128 v[178:181], v0 offset:3072
	s_waitcnt lgkmcnt(0)
	v_mfma_f32_16x16x32_bf16 v[98:101], v[130:133], v[138:141], v[98:101]
	v_and_b32_e32 v197, 63, v136
	v_ashrrev_i32_e32 v236, 6, v136
	v_mfma_f32_16x16x32_bf16 v[94:97], v[142:145], v[138:141], v[94:97]
	v_mfma_f32_16x16x32_bf16 v[90:93], v[150:153], v[138:141], v[90:93]
	v_mfma_f32_16x16x32_bf16 v[86:89], v[154:157], v[138:141], v[86:89]
	v_mfma_f32_16x16x32_bf16 v[82:85], v[158:161], v[138:141], v[82:85]
	v_mfma_f32_16x16x32_bf16 v[78:81], v[162:165], v[138:141], v[78:81]
	v_mfma_f32_16x16x32_bf16 v[74:77], v[166:169], v[138:141], v[74:77]
	v_mfma_f32_16x16x32_bf16 v[70:73], v[170:173], v[138:141], v[70:73]
	v_mfma_f32_16x16x32_bf16 v[126:129], v[130:133], v[146:149], v[126:129]
	v_mfma_f32_16x16x32_bf16 v[122:125], v[142:145], v[146:149], v[122:125]
	v_mfma_f32_16x16x32_bf16 v[118:121], v[150:153], v[146:149], v[118:121]
	v_mfma_f32_16x16x32_bf16 v[114:117], v[154:157], v[146:149], v[114:117]
	v_mfma_f32_16x16x32_bf16 v[110:113], v[158:161], v[146:149], v[110:113]
	v_mfma_f32_16x16x32_bf16 v[106:109], v[162:165], v[146:149], v[106:109]
	v_mfma_f32_16x16x32_bf16 v[102:105], v[166:169], v[146:149], v[102:105]
	v_mfma_f32_16x16x32_bf16 v[66:69], v[170:173], v[146:149], v[66:69]
	v_mfma_f32_16x16x32_bf16 v[34:37], v[130:133], v[174:177], v[34:37]
	v_mfma_f32_16x16x32_bf16 v[30:33], v[142:145], v[174:177], v[30:33]
	v_mfma_f32_16x16x32_bf16 v[26:29], v[150:153], v[174:177], v[26:29]
	v_mfma_f32_16x16x32_bf16 v[22:25], v[154:157], v[174:177], v[22:25]
	v_mfma_f32_16x16x32_bf16 v[18:21], v[158:161], v[174:177], v[18:21]
	v_mfma_f32_16x16x32_bf16 v[14:17], v[162:165], v[174:177], v[14:17]
	v_mfma_f32_16x16x32_bf16 v[10:13], v[166:169], v[174:177], v[10:13]
	v_mfma_f32_16x16x32_bf16 v[6:9], v[170:173], v[174:177], v[6:9]
	v_mfma_f32_16x16x32_bf16 v[62:65], v[130:133], v[178:181], v[62:65]
	v_mfma_f32_16x16x32_bf16 v[58:61], v[142:145], v[178:181], v[58:61]
	v_mfma_f32_16x16x32_bf16 v[54:57], v[150:153], v[178:181], v[54:57]
	v_mfma_f32_16x16x32_bf16 v[50:53], v[154:157], v[178:181], v[50:53]
	v_mfma_f32_16x16x32_bf16 v[46:49], v[158:161], v[178:181], v[46:49]
	v_mfma_f32_16x16x32_bf16 v[42:45], v[162:165], v[178:181], v[42:45]
	v_mfma_f32_16x16x32_bf16 v[38:41], v[166:169], v[178:181], v[38:41]
	v_mfma_f32_16x16x32_bf16 v[2:5], v[170:173], v[178:181], v[2:5]
	s_lshl_b32 s6, s34, 4
	s_andn2_b32 s6, s6, 31
	s_ashr_i32 s7, s6, 31
	s_lshl_b64 s[6:7], s[6:7], 13
	s_add_u32 s6, s56, s6
	s_addc_u32 s7, s57, s7
	s_lshl_b32 s8, s34, 12
	s_and_b32 s8, s8, 0x1000
	s_add_u32 s78, s6, s8
	v_cndmask_b32_e64 v0, 0, 1, s[10:11]
	s_addc_u32 s79, s7, 0
	s_mov_b64 s[8:9], -1
	v_cmp_ne_u32_e64 s[6:7], 1, v0
	s_andn2_b64 vcc, exec, s[10:11]
	v_lshlrev_b32_e32 v194, 3, v197
	v_lshlrev_b32_e32 v133, 3, v236
	v_lshlrev_b32_e32 v132, 4, v197
	s_waitcnt vmcnt(0)
	s_barrier
	s_cbranch_vccnz .LBB0_104
	v_lshlrev_b32_e32 v241, 3, v236
	v_readlane_b32 s8, v244, 54
	v_lshlrev_b32_e32 v240, 4, v197
	v_mov_b32_e32 v195, v1
	v_add_u32_e32 v238, s8, v241
	v_add_u32_e32 v134, 0, v240
	s_mov_b32 s8, 0
	v_lshlrev_b32_e32 v130, 1, v194
	v_mov_b32_e32 v135, v238

; DI int opaque_tid() { int t = threadIdx.x; asm volatile("" : "+v"(t)); return t; }
;     constexpr int WM = BM / WR, WN = BN / WC, MT = WM / 16, NT = WN / 16, ROWS = BM + BN, NCH = ROWS * 4, NIT = (NCH + 511) / 512, BUF = ROWS * 64, KT = 32;
;     constexpr int NTS = NT / NSEG, D = NST - 1;
;     static_assert(D == 1 || (NCH % 512 == 0), "deep ring needs a uniform per-thread load count");
;     const int tid = opaque_tid(), lane = tid & 63, wid = tid >> 6, wr = wid / WC, wc = wid % WC, l15 = lane & 15, quad = lane >> 4;
;     const int lrow = tid >> 2, lc = tid & 3;
;     const int lcg = lc ^ ((0 - (tid >> 4)) & 3);
;     const int rsw = (quad ^ ((0 - (l15 >> 2)) & 3)) << 4;
; #pragma unroll
;     for (int mt = 0; mt < MT; ++mt)
; #pragma unroll
;         for (int nt = 0; nt < NT; ++nt) acc[mt][nt] = (f32x4){0.f, 0.f, 0.f, 0.f};
;     const unsigned loff = (unsigned)(lrow * 64 + lcg * 16);
;     const int koff = (int)((blockIdx.x >> 3) + (blockIdx.x & 7) * 4) & (KT - 1);
;     auto issue_one = [&](int kt, int b, int i) {
;         const int row = lrow + 128 * i;
;         if ((NCH % 512 == 0) || (i < NCH / 512) || row < ROWS) {
;             const int kq = (kt + koff) & (KT - 1);
;             const char* ua = (const char*)A + (size_t)((DBG & 1) ? 0 : kq) * (BM * 64);
;             const char* ub = (const char*)Bt + (size_t)((DBG & 2) ? 0 : kq) * ((size_t)ldbk * 2);
;             const char* src;
;             if (BM % 128 == 0) src = (i < BM / 128) ? (ua + i * 8192 + loff) : (ub + (i * 128 - BM) * 64 + loff);
;             else if (i == 0) src = (lrow < BM) ? (ua + loff) : (ub + loff - BM * 64);
;             else src = ub + (i * 128 - BM) * 64 + loff;
;             __builtin_amdgcn_global_load_lds((const unsigned*)src, (unsigned*)(lds + b * BUF + i * 8192 + tid * 16), 16, 0, 0);
;         }
;     };
.LBB0_378:
	s_or_b64 exec, exec, s[28:29]
	v_ashrrev_i32_e32 v3, 6, v2
	v_lshrrev_b32_e32 v4, 29, v3
	v_add_u32_e32 v4, v3, v4
	v_lshlrev_b32_e32 v6, 2, v2
	v_ashrrev_i32_e32 v4, 3, v4
	v_and_b32_e32 v6, 48, v6
	v_mul_i32_i24_e32 v5, 8, v4
	v_sub_u32_e32 v6, 0, v6
	v_sub_u32_e32 v3, v3, v5
	v_bitop3_b32 v5, v2, 48, v6 bitop3:0x48
	v_lshlrev_b32_e32 v2, 6, v2
	v_and_b32_e32 v2, 0x3c0, v2
	v_lshl_or_b32 v141, v3, 13, v2
	v_lshl_or_b32 v139, v4, 12, v2
	v_mov_b32_e32 v2, 0
	s_mov_b32 s28, 0
	v_add_u32_e32 v140, 0, v5
	v_lshl_add_u64 v[130:131], s[8:9], 0, v[0:1]
	v_lshl_add_u64 v[132:133], s[18:19], 0, v[0:1]
	s_mov_b32 s29, 1
	v_readlane_b32 s46, v243, 23
	s_mov_b32 s47, 1
	v_mov_b32_e32 v3, v2
	v_mov_b32_e32 v4, v2
	v_mov_b32_e32 v5, v2
	v_mov_b32_e32 v38, v2
	v_mov_b32_e32 v39, v2
	v_mov_b32_e32 v40, v2
	v_mov_b32_e32 v41, v2
	v_mov_b32_e32 v42, v2
	v_mov_b32_e32 v43, v2
	v_mov_b32_e32 v44, v2
	v_mov_b32_e32 v45, v2
	v_mov_b32_e32 v46, v2
	v_mov_b32_e32 v47, v2
	v_mov_b32_e32 v48, v2
	v_mov_b32_e32 v49, v2
	v_mov_b32_e32 v50, v2
	v_mov_b32_e32 v51, v2
	v_mov_b32_e32 v52, v2
	v_mov_b32_e32 v53, v2
	v_mov_b32_e32 v54, v2
	v_mov_b32_e32 v55, v2
	v_mov_b32_e32 v56, v2
	v_mov_b32_e32 v57, v2
	v_mov_b32_e32 v58, v2
	v_mov_b32_e32 v59, v2
	v_mov_b32_e32 v60, v2
	v_mov_b32_e32 v61, v2
	v_mov_b32_e32 v62, v2
	v_mov_b32_e32 v63, v2
	v_mov_b32_e32 v64, v2
	v_mov_b32_e32 v65, v2
	v_mov_b32_e32 v6, v2
	v_mov_b32_e32 v7, v2
	v_mov_b32_e32 v8, v2
	v_mov_b32_e32 v9, v2
	v_mov_b32_e32 v10, v2
	v_mov_b32_e32 v11, v2
	v_mov_b32_e32 v12, v2
	v_mov_b32_e32 v13, v2
	v_mov_b32_e32 v14, v2
	v_mov_b32_e32 v15, v2
	v_mov_b32_e32 v16, v2
	v_mov_b32_e32 v17, v2
	v_mov_b32_e32 v18, v2
	v_mov_b32_e32 v19, v2
	v_mov_b32_e32 v20, v2
	v_mov_b32_e32 v21, v2
	v_mov_b32_e32 v22, v2
	v_mov_b32_e32 v23, v2
	v_mov_b32_e32 v24, v2
	v_mov_b32_e32 v25, v2
	v_mov_b32_e32 v26, v2
	v_mov_b32_e32 v27, v2
	v_mov_b32_e32 v28, v2
	v_mov_b32_e32 v29, v2
	v_mov_b32_e32 v30, v2
	v_mov_b32_e32 v31, v2
	v_mov_b32_e32 v32, v2
	v_mov_b32_e32 v33, v2
	v_mov_b32_e32 v34, v2
	v_mov_b32_e32 v35, v2
	v_mov_b32_e32 v36, v2
	v_mov_b32_e32 v37, v2
	v_mov_b32_e32 v66, v2
	v_mov_b32_e32 v67, v2
	v_mov_b32_e32 v68, v2
	v_mov_b32_e32 v69, v2
	v_mov_b32_e32 v102, v2
	v_mov_b32_e32 v103, v2
	v_mov_b32_e32 v104, v2
	v_mov_b32_e32 v105, v2
	v_mov_b32_e32 v106, v2
	v_mov_b32_e32 v107, v2
	v_mov_b32_e32 v108, v2
	v_mov_b32_e32 v109, v2
	v_mov_b32_e32 v110, v2
	v_mov_b32_e32 v111, v2
	v_mov_b32_e32 v112, v2
	v_mov_b32_e32 v113, v2
	v_mov_b32_e32 v114, v2
	v_mov_b32_e32 v115, v2
	v_mov_b32_e32 v116, v2
	v_mov_b32_e32 v117, v2
	v_mov_b32_e32 v118, v2
	v_mov_b32_e32 v119, v2
	v_mov_b32_e32 v120, v2
	v_mov_b32_e32 v121, v2
	v_mov_b32_e32 v122, v2
	v_mov_b32_e32 v123, v2
	v_mov_b32_e32 v124, v2
	v_mov_b32_e32 v125, v2
	v_mov_b32_e32 v126, v2
	v_mov_b32_e32 v127, v2
	v_mov_b32_e32 v128, v2
	v_mov_b32_e32 v129, v2
	v_mov_b32_e32 v70, v2
	v_mov_b32_e32 v71, v2
	v_mov_b32_e32 v72, v2
	v_mov_b32_e32 v73, v2
	v_mov_b32_e32 v74, v2
	v_mov_b32_e32 v75, v2
	v_mov_b32_e32 v76, v2
	v_mov_b32_e32 v77, v2
	v_mov_b32_e32 v78, v2
	v_mov_b32_e32 v79, v2
	v_mov_b32_e32 v80, v2
	v_mov_b32_e32 v81, v2
	v_mov_b32_e32 v82, v2
	v_mov_b32_e32 v83, v2
	v_mov_b32_e32 v84, v2
	v_mov_b32_e32 v85, v2
	v_mov_b32_e32 v86, v2
	v_mov_b32_e32 v87, v2
	v_mov_b32_e32 v88, v2
	v_mov_b32_e32 v89, v2
	v_mov_b32_e32 v90, v2
	v_mov_b32_e32 v91, v2
	v_mov_b32_e32 v92, v2
	v_mov_b32_e32 v93, v2
	v_mov_b32_e32 v94, v2
	v_mov_b32_e32 v95, v2
	v_mov_b32_e32 v96, v2
	v_mov_b32_e32 v97, v2
	v_mov_b32_e32 v98, v2
	v_mov_b32_e32 v99, v2
	v_mov_b32_e32 v100, v2
	v_mov_b32_e32 v101, v2
	v_readfirstlane_b32 s40, v212
	s_nop 3
	s_cmp_lt_u32 s40, 0x100
	s_cbranch_scc0 .Lpo2_c_entry
	s_cmp_lt_u32 s40, 0x80
	s_cselect_b32 s72, 1, 0
	s_lshl_b32 s46, s40, 4
	v_add_u32_e32 v199, s46, v0
	s_lshl_b32 s40, s40, 5
	v_readfirstlane_b32 s46, v130
	v_readfirstlane_b32 s47, v131
	v_readfirstlane_b32 s8, v0
	s_nop 3
	s_sub_u32 vcc_lo, s46, s8
	s_subb_u32 vcc_hi, s47, 0
	s_mov_b32 s29, 1
	s_add_i32 s46, s33, s29
	s_and_b32 s46, s46, 31
	s_lshl_b32 s8, s46, 16
	s_lshl_b32 s46, s46, 12
	s_add_u32 s46, vcc_lo, s46
	s_addc_u32 s47, vcc_hi, 0
	s_add_u32 s8, s18, s8
	s_addc_u32 s9, s19, 0
	s_sub_u32 s8, s8, 0x1000
	s_subb_u32 s9, s9, 0
	s_bitcmp1_b32 s29, 0
	s_cselect_b32 m0, 0x11000, 0
	s_add_u32 m0, m0, s40
	s_cmp_lg_u32 s72, 0
	s_cbranch_scc0 .Lpo2_s0b_1
	global_load_lds_dwordx4 v199, s[46:47]
	global_load_lds_dwordx4 v199, s[46:47] offset:1024
	s_branch .Lpo2_s0d_1
;     ...
;     auto issue_one = [&](int kt, int b, int i) {
;         const int row = lrow + 128 * i;
;         if ((NCH % 512 == 0) || (i < NCH / 512) || row < ROWS) {
;             const int kq = (kt + koff) & (KT - 1);
;             const char* ua = (const char*)A + (size_t)((DBG & 1) ? 0 : kq) * (BM * 64);
;             const char* ub = (const char*)Bt + (size_t)((DBG & 2) ? 0 : kq) * ((size_t)ldbk * 2);
;             const char* src;
;             if (BM % 128 == 0) src = (i < BM / 128) ? (ua + i * 8192 + loff) : (ub + (i * 128 - BM) * 64 + loff);
;             else if (i == 0) src = (lrow < BM) ? (ua + loff) : (ub + loff - BM * 64);
;             else src = ub + (i * 128 - BM) * 64 + loff;
;             __builtin_amdgcn_global_load_lds((const unsigned*)src, (unsigned*)(lds + b * BUF + i * 8192 + tid * 16), 16, 0, 0);
;         }
;     };
;     auto issue = [&](int kt, int b) {
; #pragma unroll
;         for (int i = 0; i < NIT; ++i) issue_one(kt, b, i);
;     };
;     auto compute = [&](int cb, bool do_issue, int ikt, int ib) {
;         const char* base = lds + cb * BUF;
;         bf16x8 af[MT], bfr[NT];
; #pragma unroll
;         for (int nt = 0; nt < NT; ++nt) {
;             const int br = BM + (nt / NTS) * (BN / NSEG) + wc * (NTS * 16) + (nt % NTS) * 16;
;             bfr[nt] = *(const bf16x8*)(base + (br + l15) * 64 + rsw);
;         }
; #pragma unroll
;         for (int mt = 0; mt < MT; ++mt) af[mt] = *(const bf16x8*)(base + (wr * WM + mt * 16 + l15) * 64 + rsw);
;         constexpr int TOT = MT * NT, PER = (TOT + NIT - 1) / NIT;
; #pragma unroll
;         for (int part = 0; part < NIT; ++part) {
; #pragma unroll
;             for (int q = 0; q < PER; ++q) {
;                 const int idx = part * PER + q;
;                 if (idx < TOT) {
;                     const int mt = idx / NT, nt = idx % NT;
;                     acc[mt][nt] = SWAP ? mfma16(bfr[nt], af[mt], acc[mt][nt]) : mfma16(af[mt], bfr[nt], acc[mt][nt]);
;                 }
;             }
;             __builtin_amdgcn_sched_barrier(0);
;             if (do_issue) issue_one(ikt, ib, part);
;             __builtin_amdgcn_sched_barrier(0);
;         }
;     };
;     __syncthreads();
; #pragma unroll
;     for (int d = 0; d < D; ++d) issue(d, d);
;     int cb = 0, ib = D;
;     for (int kt = 0; kt < KT; ++kt) {
.Lpo2_s0b_1:
	global_load_lds_dwordx4 v199, s[8:9]
	global_load_lds_dwordx4 v199, s[8:9] offset:1024
.Lpo2_s0d_1:
	s_add_u32 s8, s8, 0x2000
	s_addc_u32 s9, s9, 0
	s_add_u32 m0, m0, 0x2000
	s_nop 0
	global_load_lds_dwordx4 v199, s[8:9]
	global_load_lds_dwordx4 v199, s[8:9] offset:1024
	s_add_u32 s8, s8, 0x2000
	s_addc_u32 s9, s9, 0
	s_add_u32 m0, m0, 0x2000
	s_nop 0
	global_load_lds_dwordx4 v199, s[8:9]
	global_load_lds_dwordx4 v199, s[8:9] offset:1024
	s_add_u32 s8, s8, 0x2000
	s_addc_u32 s9, s9, 0
	s_add_u32 m0, m0, 0x2000
	s_nop 0
	global_load_lds_dwordx4 v199, s[8:9]
	global_load_lds_dwordx4 v199, s[8:9] offset:1024
	s_add_u32 s8, s8, 0x2000
	s_addc_u32 s9, s9, 0
	s_add_u32 m0, m0, 0x2000
	s_nop 0
	global_load_lds_dwordx4 v199, s[8:9]
	global_load_lds_dwordx4 v199, s[8:9] offset:1024
	s_add_u32 s8, s8, 0x2000
	s_addc_u32 s9, s9, 0
	s_add_u32 m0, m0, 0x2000
	s_nop 0
	global_load_lds_dwordx4 v199, s[8:9]
	global_load_lds_dwordx4 v199, s[8:9] offset:1024
	s_add_u32 s8, s8, 0x2000
	s_addc_u32 s9, s9, 0
	s_add_u32 m0, m0, 0x2000
	s_nop 0
	global_load_lds_dwordx4 v199, s[8:9]
	global_load_lds_dwordx4 v199, s[8:9] offset:1024
	s_add_u32 s8, s8, 0x2000
	s_addc_u32 s9, s9, 0
	s_add_u32 m0, m0, 0x2000
	s_nop 0
	global_load_lds_dwordx4 v199, s[8:9]
	global_load_lds_dwordx4 v199, s[8:9] offset:1024
	s_add_u32 s8, s8, 0x2000
	s_addc_u32 s9, s9, 0
	s_lshr_b32 s46, s40, 1
	s_bitcmp1_b32 s29, 0
	s_cselect_b32 m0, 0x11000, 0
	s_add_u32 m0, m0, s46
	s_add_u32 m0, m0, 0x10000
	s_nop 0
	global_load_lds_dwordx4 v0, s[8:9]
	s_mov_b32 s29, 2
	s_waitcnt vmcnt(17)
	s_barrier
	v_add_u32_e32 v197, v140, v141
	v_add_u32_e32 v196, v140, v139
	ds_read_b128 v[146:149], v196
	ds_read_b128 v[154:157], v196 offset:1024
	ds_read_b128 v[182:185], v196 offset:2048
	ds_read_b128 v[142:145], v197 offset:4096
	ds_read_b128 v[150:153], v197 offset:5120
	ds_read_b128 v[158:161], v197 offset:6144
	ds_read_b128 v[162:165], v197 offset:7168
	ds_read_b128 v[166:169], v197 offset:8192
	ds_read_b128 v[170:173], v197 offset:9216
	ds_read_b128 v[174:177], v197 offset:10240
	ds_read_b128 v[178:181], v197 offset:11264
	ds_read_b128 v[186:189], v196 offset:3072
.Lpo2_l_loop:
	s_bitcmp1_b32 s29, 0
	s_cselect_b32 s46, 0, 0x11000
	v_add_u32_e32 v198, s46, v140
	v_add_u32_e32 v197, v198, v141
	v_add_u32_e32 v196, v198, v139
	s_waitcnt lgkmcnt(8)
	v_mfma_f32_16x16x32_bf16 v[98:101], v[142:145], v[146:149], v[98:101]
	s_waitcnt lgkmcnt(7)
	v_mfma_f32_16x16x32_bf16 v[94:97], v[150:153], v[146:149], v[94:97]
	s_waitcnt lgkmcnt(6)
	v_mfma_f32_16x16x32_bf16 v[90:93], v[158:161], v[146:149], v[90:93]
	s_waitcnt lgkmcnt(5)
	v_mfma_f32_16x16x32_bf16 v[86:89], v[162:165], v[146:149], v[86:89]
	s_waitcnt lgkmcnt(4)
	v_mfma_f32_16x16x32_bf16 v[82:85], v[166:169], v[146:149], v[82:85]
	s_waitcnt lgkmcnt(3)
	v_mfma_f32_16x16x32_bf16 v[78:81], v[170:173], v[146:149], v[78:81]
	s_waitcnt lgkmcnt(2)
	v_mfma_f32_16x16x32_bf16 v[74:77], v[174:177], v[146:149], v[74:77]
	s_waitcnt lgkmcnt(1)
	v_mfma_f32_16x16x32_bf16 v[70:73], v[178:181], v[146:149], v[70:73]
	s_waitcnt vmcnt(0) lgkmcnt(0)
	s_barrier
	ds_read_b128 v[146:149], v196
	s_add_i32 s46, s33, s29
	s_and_b32 s46, s46, 31
	s_lshl_b32 s8, s46, 16
	s_lshl_b32 s46, s46, 12
	s_add_u32 s46, vcc_lo, s46
	s_addc_u32 s47, vcc_hi, 0
	s_add_u32 s8, s18, s8
	s_addc_u32 s9, s19, 0
	s_sub_u32 s8, s8, 0x1000
	s_subb_u32 s9, s9, 0
	s_bitcmp1_b32 s29, 0
	s_cselect_b32 m0, 0x11000, 0
	s_add_u32 m0, m0, s40
	s_cmp_lg_u32 s72, 0
	s_cbranch_scc0 .Lpo2_s0b_2
	global_load_lds_dwordx4 v199, s[46:47]
	global_load_lds_dwordx4 v199, s[46:47] offset:1024
	s_branch .Lpo2_s0d_2

; DI f32x4 mfma16(bf16x8 a, bf16x8 b, f32x4 c) { return __builtin_amdgcn_mfma_f32_16x16x32_bf16(a, b, c, 0, 0, 0); }
; template <int N> DI void wait_vm() { asm volatile("s_waitcnt vmcnt(%0)" ::"n"(N) : "memory"); }
; DI void raw_barrier() { asm volatile("" ::: "memory"); __builtin_amdgcn_s_barrier(); asm volatile("" ::: "memory"); }
;     ...
;     auto compute = [&](int cb, bool do_issue, int ikt, int ib) {
;         const char* base = lds + cb * BUF;
;         bf16x8 af[MT], bfr[NT];
; #pragma unroll
;         for (int nt = 0; nt < NT; ++nt) {
;             const int br = BM + (nt / NTS) * (BN / NSEG) + wc * (NTS * 16) + (nt % NTS) * 16;
;             bfr[nt] = *(const bf16x8*)(base + (br + l15) * 64 + rsw);
;         }
; #pragma unroll
;         for (int mt = 0; mt < MT; ++mt) af[mt] = *(const bf16x8*)(base + (wr * WM + mt * 16 + l15) * 64 + rsw);
;         constexpr int TOT = MT * NT, PER = (TOT + NIT - 1) / NIT;
; #pragma unroll
;         for (int part = 0; part < NIT; ++part) {
; #pragma unroll
;             for (int q = 0; q < PER; ++q) {
;                 const int idx = part * PER + q;
;                 if (idx < TOT) {
;                     const int mt = idx / NT, nt = idx % NT;
;                     acc[mt][nt] = SWAP ? mfma16(bfr[nt], af[mt], acc[mt][nt]) : mfma16(af[mt], bfr[nt], acc[mt][nt]);
;                 }
;             }
;             __builtin_amdgcn_sched_barrier(0);
;             if (do_issue) issue_one(ikt, ib, part);
;             __builtin_amdgcn_sched_barrier(0);
;         }
;     };
;     __syncthreads();
; #pragma unroll
;     for (int d = 0; d < D; ++d) issue(d, d);
;     int cb = 0, ib = D;
;     for (int kt = 0; kt < KT; ++kt) {
;         if (D > 1 && kt + D - 1 < KT) wait_vm<(D - 1) * NIT>(); else wait_vm<0>();
;         raw_barrier();
;         compute(cb, kt + D < KT, kt + D, ib);
;         cb = (cb + 1 == NST) ? 0 : cb + 1;
;         ib = (ib + 1 == NST) ? 0 : ib + 1;
;     }
.Lpo2_s0d_2:
	v_mfma_f32_16x16x32_bf16 v[126:129], v[142:145], v[154:157], v[126:129]
	v_mfma_f32_16x16x32_bf16 v[122:125], v[150:153], v[154:157], v[122:125]
	v_mfma_f32_16x16x32_bf16 v[118:121], v[158:161], v[154:157], v[118:121]
	s_add_u32 s8, s8, 0x2000
	s_addc_u32 s9, s9, 0
	s_add_u32 m0, m0, 0x2000
	s_nop 0
	global_load_lds_dwordx4 v199, s[8:9]
	global_load_lds_dwordx4 v199, s[8:9] offset:1024
	v_mfma_f32_16x16x32_bf16 v[114:117], v[162:165], v[154:157], v[114:117]
	v_mfma_f32_16x16x32_bf16 v[110:113], v[166:169], v[154:157], v[110:113]
	s_add_u32 s8, s8, 0x2000
	s_addc_u32 s9, s9, 0
	s_add_u32 m0, m0, 0x2000
	s_nop 0
	global_load_lds_dwordx4 v199, s[8:9]
	global_load_lds_dwordx4 v199, s[8:9] offset:1024
	v_mfma_f32_16x16x32_bf16 v[106:109], v[170:173], v[154:157], v[106:109]
	v_mfma_f32_16x16x32_bf16 v[102:105], v[174:177], v[154:157], v[102:105]
	v_mfma_f32_16x16x32_bf16 v[66:69], v[178:181], v[154:157], v[66:69]
	s_add_u32 s8, s8, 0x2000
	s_addc_u32 s9, s9, 0
	s_add_u32 m0, m0, 0x2000
	s_nop 0
	global_load_lds_dwordx4 v199, s[8:9]
	global_load_lds_dwordx4 v199, s[8:9] offset:1024
	ds_read_b128 v[154:157], v196 offset:1024
	v_mfma_f32_16x16x32_bf16 v[34:37], v[142:145], v[182:185], v[34:37]
	v_mfma_f32_16x16x32_bf16 v[30:33], v[150:153], v[182:185], v[30:33]
	v_mfma_f32_16x16x32_bf16 v[26:29], v[158:161], v[182:185], v[26:29]
	s_add_u32 s8, s8, 0x2000
	s_addc_u32 s9, s9, 0
	s_add_u32 m0, m0, 0x2000
	s_nop 0
	global_load_lds_dwordx4 v199, s[8:9]
	global_load_lds_dwordx4 v199, s[8:9] offset:1024
	v_mfma_f32_16x16x32_bf16 v[22:25], v[162:165], v[182:185], v[22:25]
	v_mfma_f32_16x16x32_bf16 v[18:21], v[166:169], v[182:185], v[18:21]
	s_add_u32 s8, s8, 0x2000
	s_addc_u32 s9, s9, 0
	s_add_u32 m0, m0, 0x2000
	s_nop 0
	global_load_lds_dwordx4 v199, s[8:9]
	global_load_lds_dwordx4 v199, s[8:9] offset:1024
	v_mfma_f32_16x16x32_bf16 v[14:17], v[170:173], v[182:185], v[14:17]
	v_mfma_f32_16x16x32_bf16 v[10:13], v[174:177], v[182:185], v[10:13]
	v_mfma_f32_16x16x32_bf16 v[6:9], v[178:181], v[182:185], v[6:9]
	s_add_u32 s8, s8, 0x2000
	s_addc_u32 s9, s9, 0
	s_add_u32 m0, m0, 0x2000
	s_nop 0
	global_load_lds_dwordx4 v199, s[8:9]
	global_load_lds_dwordx4 v199, s[8:9] offset:1024
	ds_read_b128 v[182:185], v196 offset:2048
	v_mfma_f32_16x16x32_bf16 v[62:65], v[142:145], v[186:189], v[62:65]
	ds_read_b128 v[142:145], v197 offset:4096
	v_mfma_f32_16x16x32_bf16 v[58:61], v[150:153], v[186:189], v[58:61]
	ds_read_b128 v[150:153], v197 offset:5120
	v_mfma_f32_16x16x32_bf16 v[54:57], v[158:161], v[186:189], v[54:57]
	ds_read_b128 v[158:161], v197 offset:6144
	s_add_u32 s8, s8, 0x2000
	s_addc_u32 s9, s9, 0
	s_add_u32 m0, m0, 0x2000
	s_nop 0
	global_load_lds_dwordx4 v199, s[8:9]
	global_load_lds_dwordx4 v199, s[8:9] offset:1024
	v_mfma_f32_16x16x32_bf16 v[50:53], v[162:165], v[186:189], v[50:53]
	ds_read_b128 v[162:165], v197 offset:7168
	v_mfma_f32_16x16x32_bf16 v[46:49], v[166:169], v[186:189], v[46:49]
	ds_read_b128 v[166:169], v197 offset:8192
	s_add_u32 s8, s8, 0x2000
	s_addc_u32 s9, s9, 0
	s_lshr_b32 s46, s40, 1
	s_bitcmp1_b32 s29, 0
	s_cselect_b32 m0, 0x11000, 0
	s_add_u32 m0, m0, s46
	s_add_u32 m0, m0, 0x10000
	s_nop 0
	global_load_lds_dwordx4 v0, s[8:9]
	v_mfma_f32_16x16x32_bf16 v[42:45], v[170:173], v[186:189], v[42:45]
	ds_read_b128 v[170:173], v197 offset:9216
	v_mfma_f32_16x16x32_bf16 v[38:41], v[174:177], v[186:189], v[38:41]
	ds_read_b128 v[174:177], v197 offset:10240
	v_mfma_f32_16x16x32_bf16 v[2:5], v[178:181], v[186:189], v[2:5]
	ds_read_b128 v[178:181], v197 offset:11264
	ds_read_b128 v[186:189], v196 offset:3072
	s_add_i32 s29, s29, 1
	s_cmp_lg_u32 s29, 32
	s_cbranch_scc1 .Lpo2_l_loop
	s_waitcnt lgkmcnt(8)
	v_mfma_f32_16x16x32_bf16 v[98:101], v[142:145], v[146:149], v[98:101]
	s_waitcnt lgkmcnt(7)
	v_mfma_f32_16x16x32_bf16 v[94:97], v[150:153], v[146:149], v[94:97]
	s_waitcnt lgkmcnt(6)
	v_mfma_f32_16x16x32_bf16 v[90:93], v[158:161], v[146:149], v[90:93]
	s_waitcnt lgkmcnt(5)
	v_mfma_f32_16x16x32_bf16 v[86:89], v[162:165], v[146:149], v[86:89]
	s_waitcnt lgkmcnt(4)
	v_mfma_f32_16x16x32_bf16 v[82:85], v[166:169], v[146:149], v[82:85]
	s_waitcnt lgkmcnt(3)
	v_mfma_f32_16x16x32_bf16 v[78:81], v[170:173], v[146:149], v[78:81]
	s_waitcnt lgkmcnt(2)
	v_mfma_f32_16x16x32_bf16 v[74:77], v[174:177], v[146:149], v[74:77]
	s_waitcnt lgkmcnt(1)
	v_mfma_f32_16x16x32_bf16 v[70:73], v[178:181], v[146:149], v[70:73]
	s_waitcnt lgkmcnt(0)
	v_mfma_f32_16x16x32_bf16 v[126:129], v[142:145], v[154:157], v[126:129]
	v_mfma_f32_16x16x32_bf16 v[122:125], v[150:153], v[154:157], v[122:125]
	v_mfma_f32_16x16x32_bf16 v[118:121], v[158:161], v[154:157], v[118:121]
	v_mfma_f32_16x16x32_bf16 v[114:117], v[162:165], v[154:157], v[114:117]
	v_mfma_f32_16x16x32_bf16 v[110:113], v[166:169], v[154:157], v[110:113]
	v_mfma_f32_16x16x32_bf16 v[106:109], v[170:173], v[154:157], v[106:109]
	v_mfma_f32_16x16x32_bf16 v[102:105], v[174:177], v[154:157], v[102:105]
	v_mfma_f32_16x16x32_bf16 v[66:69], v[178:181], v[154:157], v[66:69]
	v_mfma_f32_16x16x32_bf16 v[34:37], v[142:145], v[182:185], v[34:37]
	v_mfma_f32_16x16x32_bf16 v[30:33], v[150:153], v[182:185], v[30:33]
	v_mfma_f32_16x16x32_bf16 v[26:29], v[158:161], v[182:185], v[26:29]
	v_mfma_f32_16x16x32_bf16 v[22:25], v[162:165], v[182:185], v[22:25]
	v_mfma_f32_16x16x32_bf16 v[18:21], v[166:169], v[182:185], v[18:21]
	v_mfma_f32_16x16x32_bf16 v[14:17], v[170:173], v[182:185], v[14:17]
	v_mfma_f32_16x16x32_bf16 v[10:13], v[174:177], v[182:185], v[10:13]
	v_mfma_f32_16x16x32_bf16 v[6:9], v[178:181], v[182:185], v[6:9]
	v_mfma_f32_16x16x32_bf16 v[62:65], v[142:145], v[186:189], v[62:65]
	v_mfma_f32_16x16x32_bf16 v[58:61], v[150:153], v[186:189], v[58:61]
	v_mfma_f32_16x16x32_bf16 v[54:57], v[158:161], v[186:189], v[54:57]
	v_mfma_f32_16x16x32_bf16 v[50:53], v[162:165], v[186:189], v[50:53]
	v_mfma_f32_16x16x32_bf16 v[46:49], v[166:169], v[186:189], v[46:49]
	v_mfma_f32_16x16x32_bf16 v[42:45], v[170:173], v[186:189], v[42:45]
	v_mfma_f32_16x16x32_bf16 v[38:41], v[174:177], v[186:189], v[38:41]
	v_mfma_f32_16x16x32_bf16 v[2:5], v[178:181], v[186:189], v[2:5]
	s_branch .Lpo2_join
; DI f32x4 mfma16(bf16x8 a, bf16x8 b, f32x4 c) { return __builtin_amdgcn_mfma_f32_16x16x32_bf16(a, b, c, 0, 0, 0); }
; template <int N> DI void wait_vm() { asm volatile("s_waitcnt vmcnt(%0)" ::"n"(N) : "memory"); }
; DI void raw_barrier() { asm volatile("" ::: "memory"); __builtin_amdgcn_s_barrier(); asm volatile("" ::: "memory"); }
;     ...
;     auto compute = [&](int cb, bool do_issue, int ikt, int ib) {
;         const char* base = lds + cb * BUF;
;         bf16x8 af[MT], bfr[NT];
; #pragma unroll
;         for (int nt = 0; nt < NT; ++nt) {
;             const int br = BM + (nt / NTS) * (BN / NSEG) + wc * (NTS * 16) + (nt % NTS) * 16;
;             bfr[nt] = *(const bf16x8*)(base + (br + l15) * 64 + rsw);
;         }
; #pragma unroll
;         for (int mt = 0; mt < MT; ++mt) af[mt] = *(const bf16x8*)(base + (wr * WM + mt * 16 + l15) * 64 + rsw);
;         constexpr int TOT = MT * NT, PER = (TOT + NIT - 1) / NIT;
; #pragma unroll
;         for (int part = 0; part < NIT; ++part) {
; #pragma unroll
;             for (int q = 0; q < PER; ++q) {
;                 const int idx = part * PER + q;
;                 if (idx < TOT) {
;                     const int mt = idx / NT, nt = idx % NT;
;                     acc[mt][nt] = SWAP ? mfma16(bfr[nt], af[mt], acc[mt][nt]) : mfma16(af[mt], bfr[nt], acc[mt][nt]);
;                 }
;             }
;             __builtin_amdgcn_sched_barrier(0);
;             if (do_issue) issue_one(ikt, ib, part);
;             __builtin_amdgcn_sched_barrier(0);
;         }
;     };
;     __syncthreads();
; #pragma unroll
;     for (int d = 0; d < D; ++d) issue(d, d);
;     int cb = 0, ib = D;
;     for (int kt = 0; kt < KT; ++kt) {
;         if (D > 1 && kt + D - 1 < KT) wait_vm<(D - 1) * NIT>(); else wait_vm<0>();
;         raw_barrier();
;         compute(cb, kt + D < KT, kt + D, ib);
;         cb = (cb + 1 == NST) ? 0 : cb + 1;
;         ib = (ib + 1 == NST) ? 0 : ib + 1;
;     }
.Lpo2_c_entry:
	s_mov_b32 s29, 2
	s_waitcnt vmcnt(0)
	s_barrier
	v_add_u32_e32 v197, v140, v141
	v_add_u32_e32 v196, v140, v139
	ds_read_b128 v[146:149], v196
	ds_read_b128 v[154:157], v196 offset:1024
	ds_read_b128 v[182:185], v196 offset:2048
	ds_read_b128 v[142:145], v197 offset:4096
	ds_read_b128 v[150:153], v197 offset:5120
	ds_read_b128 v[158:161], v197 offset:6144
	ds_read_b128 v[162:165], v197 offset:7168
	ds_read_b128 v[166:169], v197 offset:8192
	ds_read_b128 v[170:173], v197 offset:9216
	ds_read_b128 v[174:177], v197 offset:10240
	ds_read_b128 v[178:181], v197 offset:11264
	ds_read_b128 v[186:189], v196 offset:3072
.Lpo2_c_loop:
	s_bitcmp1_b32 s29, 0
	s_cselect_b32 s46, 0, 0x11000
	v_add_u32_e32 v198, s46, v140
	v_add_u32_e32 v197, v198, v141
	v_add_u32_e32 v196, v198, v139
	s_waitcnt lgkmcnt(8)
	v_mfma_f32_16x16x32_bf16 v[98:101], v[142:145], v[146:149], v[98:101]
	s_waitcnt lgkmcnt(7)
	v_mfma_f32_16x16x32_bf16 v[94:97], v[150:153], v[146:149], v[94:97]
	s_waitcnt lgkmcnt(6)
	v_mfma_f32_16x16x32_bf16 v[90:93], v[158:161], v[146:149], v[90:93]
	s_waitcnt lgkmcnt(5)
	v_mfma_f32_16x16x32_bf16 v[86:89], v[162:165], v[146:149], v[86:89]
	s_waitcnt lgkmcnt(4)
	v_mfma_f32_16x16x32_bf16 v[82:85], v[166:169], v[146:149], v[82:85]
	s_waitcnt lgkmcnt(3)
	v_mfma_f32_16x16x32_bf16 v[78:81], v[170:173], v[146:149], v[78:81]
	s_waitcnt lgkmcnt(2)
	v_mfma_f32_16x16x32_bf16 v[74:77], v[174:177], v[146:149], v[74:77]
	s_waitcnt lgkmcnt(1)
	v_mfma_f32_16x16x32_bf16 v[70:73], v[178:181], v[146:149], v[70:73]
	s_waitcnt vmcnt(0) lgkmcnt(0)
	s_barrier
	ds_read_b128 v[146:149], v196
	v_mfma_f32_16x16x32_bf16 v[126:129], v[142:145], v[154:157], v[126:129]
	v_mfma_f32_16x16x32_bf16 v[122:125], v[150:153], v[154:157], v[122:125]
	v_mfma_f32_16x16x32_bf16 v[118:121], v[158:161], v[154:157], v[118:121]
	v_mfma_f32_16x16x32_bf16 v[114:117], v[162:165], v[154:157], v[114:117]
	v_mfma_f32_16x16x32_bf16 v[110:113], v[166:169], v[154:157], v[110:113]
	v_mfma_f32_16x16x32_bf16 v[106:109], v[170:173], v[154:157], v[106:109]
	v_mfma_f32_16x16x32_bf16 v[102:105], v[174:177], v[154:157], v[102:105]
	v_mfma_f32_16x16x32_bf16 v[66:69], v[178:181], v[154:157], v[66:69]
	ds_read_b128 v[154:157], v196 offset:1024
	v_mfma_f32_16x16x32_bf16 v[34:37], v[142:145], v[182:185], v[34:37]
	v_mfma_f32_16x16x32_bf16 v[30:33], v[150:153], v[182:185], v[30:33]
	v_mfma_f32_16x16x32_bf16 v[26:29], v[158:161], v[182:185], v[26:29]
	v_mfma_f32_16x16x32_bf16 v[22:25], v[162:165], v[182:185], v[22:25]
	v_mfma_f32_16x16x32_bf16 v[18:21], v[166:169], v[182:185], v[18:21]
	v_mfma_f32_16x16x32_bf16 v[14:17], v[170:173], v[182:185], v[14:17]
	v_mfma_f32_16x16x32_bf16 v[10:13], v[174:177], v[182:185], v[10:13]
	v_mfma_f32_16x16x32_bf16 v[6:9], v[178:181], v[182:185], v[6:9]
	ds_read_b128 v[182:185], v196 offset:2048
	v_mfma_f32_16x16x32_bf16 v[62:65], v[142:145], v[186:189], v[62:65]
	ds_read_b128 v[142:145], v197 offset:4096
	v_mfma_f32_16x16x32_bf16 v[58:61], v[150:153], v[186:189], v[58:61]
	ds_read_b128 v[150:153], v197 offset:5120
	v_mfma_f32_16x16x32_bf16 v[54:57], v[158:161], v[186:189], v[54:57]
	ds_read_b128 v[158:161], v197 offset:6144
	v_mfma_f32_16x16x32_bf16 v[50:53], v[162:165], v[186:189], v[50:53]
	ds_read_b128 v[162:165], v197 offset:7168
	v_mfma_f32_16x16x32_bf16 v[46:49], v[166:169], v[186:189], v[46:49]
	ds_read_b128 v[166:169], v197 offset:8192
	v_mfma_f32_16x16x32_bf16 v[42:45], v[170:173], v[186:189], v[42:45]
	ds_read_b128 v[170:173], v197 offset:9216
	v_mfma_f32_16x16x32_bf16 v[38:41], v[174:177], v[186:189], v[38:41]
	ds_read_b128 v[174:177], v197 offset:10240
	v_mfma_f32_16x16x32_bf16 v[2:5], v[178:181], v[186:189], v[2:5]
	ds_read_b128 v[178:181], v197 offset:11264
	ds_read_b128 v[186:189], v196 offset:3072
	s_add_i32 s29, s29, 1
	s_cmp_lg_u32 s29, 32
	s_cbranch_scc1 .Lpo2_c_loop
	s_waitcnt lgkmcnt(8)
	v_mfma_f32_16x16x32_bf16 v[98:101], v[142:145], v[146:149], v[98:101]
	s_waitcnt lgkmcnt(7)
	v_mfma_f32_16x16x32_bf16 v[94:97], v[150:153], v[146:149], v[94:97]
	s_waitcnt lgkmcnt(6)
	v_mfma_f32_16x16x32_bf16 v[90:93], v[158:161], v[146:149], v[90:93]
	s_waitcnt lgkmcnt(5)
	v_mfma_f32_16x16x32_bf16 v[86:89], v[162:165], v[146:149], v[86:89]
	s_waitcnt lgkmcnt(4)
	v_mfma_f32_16x16x32_bf16 v[82:85], v[166:169], v[146:149], v[82:85]
	s_waitcnt lgkmcnt(3)
	v_mfma_f32_16x16x32_bf16 v[78:81], v[170:173], v[146:149], v[78:81]
	s_waitcnt lgkmcnt(2)
	v_mfma_f32_16x16x32_bf16 v[74:77], v[174:177], v[146:149], v[74:77]
	s_waitcnt lgkmcnt(1)
	v_mfma_f32_16x16x32_bf16 v[70:73], v[178:181], v[146:149], v[70:73]
	s_waitcnt lgkmcnt(0)
	v_mfma_f32_16x16x32_bf16 v[126:129], v[142:145], v[154:157], v[126:129]
	v_mfma_f32_16x16x32_bf16 v[122:125], v[150:153], v[154:157], v[122:125]
	v_mfma_f32_16x16x32_bf16 v[118:121], v[158:161], v[154:157], v[118:121]
	v_mfma_f32_16x16x32_bf16 v[114:117], v[162:165], v[154:157], v[114:117]
	v_mfma_f32_16x16x32_bf16 v[110:113], v[166:169], v[154:157], v[110:113]
	v_mfma_f32_16x16x32_bf16 v[106:109], v[170:173], v[154:157], v[106:109]
	v_mfma_f32_16x16x32_bf16 v[102:105], v[174:177], v[154:157], v[102:105]
	v_mfma_f32_16x16x32_bf16 v[66:69], v[178:181], v[154:157], v[66:69]
	v_mfma_f32_16x16x32_bf16 v[34:37], v[142:145], v[182:185], v[34:37]
	v_mfma_f32_16x16x32_bf16 v[30:33], v[150:153], v[182:185], v[30:33]
	v_mfma_f32_16x16x32_bf16 v[26:29], v[158:161], v[182:185], v[26:29]
	v_mfma_f32_16x16x32_bf16 v[22:25], v[162:165], v[182:185], v[22:25]
	v_mfma_f32_16x16x32_bf16 v[18:21], v[166:169], v[182:185], v[18:21]
	v_mfma_f32_16x16x32_bf16 v[14:17], v[170:173], v[182:185], v[14:17]
	v_mfma_f32_16x16x32_bf16 v[10:13], v[174:177], v[182:185], v[10:13]
	v_mfma_f32_16x16x32_bf16 v[6:9], v[178:181], v[182:185], v[6:9]
	v_mfma_f32_16x16x32_bf16 v[62:65], v[142:145], v[186:189], v[62:65]
	v_mfma_f32_16x16x32_bf16 v[58:61], v[150:153], v[186:189], v[58:61]
	v_mfma_f32_16x16x32_bf16 v[54:57], v[158:161], v[186:189], v[54:57]
	v_mfma_f32_16x16x32_bf16 v[50:53], v[162:165], v[186:189], v[50:53]
	v_mfma_f32_16x16x32_bf16 v[46:49], v[166:169], v[186:189], v[46:49]
	v_mfma_f32_16x16x32_bf16 v[42:45], v[170:173], v[186:189], v[42:45]
	v_mfma_f32_16x16x32_bf16 v[38:41], v[174:177], v[186:189], v[38:41]
	v_mfma_f32_16x16x32_bf16 v[2:5], v[178:181], v[186:189], v[2:5]
; template <int N> DI void wait_vm() { asm volatile("s_waitcnt vmcnt(%0)" ::"n"(N) : "memory"); }
; DI void raw_barrier() { asm volatile("" ::: "memory"); __builtin_amdgcn_s_barrier(); asm volatile("" ::: "memory"); }
;     ...
;     __syncthreads();
; #pragma unroll
;     for (int d = 0; d < D; ++d) issue(d, d);
;     int cb = 0, ib = D;
;     for (int kt = 0; kt < KT; ++kt) {
;         if (D > 1 && kt + D - 1 < KT) wait_vm<(D - 1) * NIT>(); else wait_vm<0>();
;         raw_barrier();
;         compute(cb, kt + D < KT, kt + D, ib);
;         cb = (cb + 1 == NST) ? 0 : cb + 1;
;         ib = (ib + 1 == NST) ? 0 : ib + 1;
;     }
;     __syncthreads();
; DI void unit_O(const Params& p, char* lds, int l, int tile, int glu_tiles, int tile_b) {
;     ...
;     gemm_main<64, 1024, 1, 8, 1, true, 2>(WS_PTR(const bf16_t, OFF_Y) + (size_t)tile * 64 * 1024, WS_PTR(const bf16_t, OFF_WOUT) + (size_t)l * 1024 * 1024, 1024 * 32, lds, acc);
;     const float* xres = (l == 0) ? p.x : WS_PTR(const float, OFF_X1);
;     const size_t r0 = (size_t)tile * 64;
;     char* XR = lds;
;     float* GB = (float*)(lds + 131072);
;     float* red = (float*)(lds + 139264);
;     const int xrot = (int)(((blockIdx.x >> 3) + (blockIdx.x & 7) * 4) & 31) * 4;
;     const bf16_t* xbres = WS_PTR(const bf16_t, OFF_XB1) + ((size_t)((tile >> 1) * 32) * 128 + (tile & 1) * 64) * 32;
.Lpo2_join:
.LBB0_382:
	s_waitcnt vmcnt(0)
	v_add_u32_e32 v0, 0x11000, v140
	s_barrier
	v_add_u32_e32 v134, v0, v141
	v_add_u32_e32 v0, v0, v139
	ds_read_b128 v[130:133], v134 offset:4096
	ds_read_b128 v[138:141], v0
	ds_read_b128 v[142:145], v134 offset:5120
	ds_read_b128 v[146:149], v0 offset:1024
	ds_read_b128 v[150:153], v134 offset:6144
	ds_read_b128 v[154:157], v134 offset:7168
	ds_read_b128 v[158:161], v134 offset:8192
	ds_read_b128 v[162:165], v134 offset:9216
	ds_read_b128 v[166:169], v134 offset:10240
	ds_read_b128 v[170:173], v134 offset:11264
	ds_read_b128 v[174:177], v0 offset:2048
	ds_read_b128 v[178:181], v0 offset:3072
	s_waitcnt lgkmcnt(0)
	v_mfma_f32_16x16x32_bf16 v[98:101], v[130:133], v[138:141], v[98:101]
	v_and_b32_e32 v197, 63, v136
	v_ashrrev_i32_e32 v236, 6, v136
	v_mfma_f32_16x16x32_bf16 v[94:97], v[142:145], v[138:141], v[94:97]
	v_mfma_f32_16x16x32_bf16 v[90:93], v[150:153], v[138:141], v[90:93]
	v_mfma_f32_16x16x32_bf16 v[86:89], v[154:157], v[138:141], v[86:89]
	v_mfma_f32_16x16x32_bf16 v[82:85], v[158:161], v[138:141], v[82:85]
	v_mfma_f32_16x16x32_bf16 v[78:81], v[162:165], v[138:141], v[78:81]
	v_mfma_f32_16x16x32_bf16 v[74:77], v[166:169], v[138:141], v[74:77]
	v_mfma_f32_16x16x32_bf16 v[70:73], v[170:173], v[138:141], v[70:73]
	v_mfma_f32_16x16x32_bf16 v[126:129], v[130:133], v[146:149], v[126:129]
	v_mfma_f32_16x16x32_bf16 v[122:125], v[142:145], v[146:149], v[122:125]
	v_mfma_f32_16x16x32_bf16 v[118:121], v[150:153], v[146:149], v[118:121]
	v_mfma_f32_16x16x32_bf16 v[114:117], v[154:157], v[146:149], v[114:117]
	v_mfma_f32_16x16x32_bf16 v[110:113], v[158:161], v[146:149], v[110:113]
	v_mfma_f32_16x16x32_bf16 v[106:109], v[162:165], v[146:149], v[106:109]
	v_mfma_f32_16x16x32_bf16 v[102:105], v[166:169], v[146:149], v[102:105]
	v_mfma_f32_16x16x32_bf16 v[66:69], v[170:173], v[146:149], v[66:69]
	v_mfma_f32_16x16x32_bf16 v[34:37], v[130:133], v[174:177], v[34:37]
	v_mfma_f32_16x16x32_bf16 v[30:33], v[142:145], v[174:177], v[30:33]
	v_mfma_f32_16x16x32_bf16 v[26:29], v[150:153], v[174:177], v[26:29]
	v_mfma_f32_16x16x32_bf16 v[22:25], v[154:157], v[174:177], v[22:25]
	v_mfma_f32_16x16x32_bf16 v[18:21], v[158:161], v[174:177], v[18:21]
	v_mfma_f32_16x16x32_bf16 v[14:17], v[162:165], v[174:177], v[14:17]
	v_mfma_f32_16x16x32_bf16 v[10:13], v[166:169], v[174:177], v[10:13]
	v_mfma_f32_16x16x32_bf16 v[6:9], v[170:173], v[174:177], v[6:9]
	v_mfma_f32_16x16x32_bf16 v[62:65], v[130:133], v[178:181], v[62:65]
	v_mfma_f32_16x16x32_bf16 v[58:61], v[142:145], v[178:181], v[58:61]
	v_mfma_f32_16x16x32_bf16 v[54:57], v[150:153], v[178:181], v[54:57]
	v_mfma_f32_16x16x32_bf16 v[50:53], v[154:157], v[178:181], v[50:53]
	v_mfma_f32_16x16x32_bf16 v[46:49], v[158:161], v[178:181], v[46:49]
	v_mfma_f32_16x16x32_bf16 v[42:45], v[162:165], v[178:181], v[42:45]
	v_mfma_f32_16x16x32_bf16 v[38:41], v[166:169], v[178:181], v[38:41]
	v_mfma_f32_16x16x32_bf16 v[2:5], v[170:173], v[178:181], v[2:5]
	s_lshl_b32 s8, s48, 4
	s_andn2_b32 s8, s8, 31
	s_ashr_i32 s9, s8, 31
	s_lshl_b64 s[8:9], s[8:9], 13
	s_add_u32 s8, s56, s8
	s_addc_u32 s9, s57, s9
	s_lshl_b32 s28, s48, 12
	s_and_b32 s28, s28, 0x1000
	s_add_u32 s46, s8, s28
	s_addc_u32 s47, s9, 0
	s_mov_b64 s[8:9], -1
	s_and_b64 vcc, exec, s[6:7]
	v_lshlrev_b32_e32 v194, 3, v197
	v_lshlrev_b32_e32 v133, 3, v236
	v_lshlrev_b32_e32 v132, 4, v197
	s_waitcnt vmcnt(0)
	s_barrier
	s_cbranch_vccnz .LBB0_386
	v_lshlrev_b32_e32 v241, 3, v236
	v_readlane_b32 s8, v244, 54
	v_lshlrev_b32_e32 v240, 4, v197
	v_mov_b32_e32 v195, v1
	v_add_u32_e32 v238, s8, v241
	v_add_u32_e32 v134, 0, v240
	s_mov_b32 s8, 0
	v_lshlrev_b32_e32 v130, 1, v194
	v_mov_b32_e32 v135, v238
